# MFMA order zz_n: accumulate chains with alternating K order so the B fragment (srcA) repeats across every chain boundary
# speedup vs baseline: 1.0056x; 1.0056x over previous
; #define PG8_STAGE(bufoff, gbase, voff) do { _Pragma("unroll") for (int _i = 0; _i < 2; ++_i) \
;         __builtin_amdgcn_global_load_lds((const unsigned*)((const char*)(gbase) + (voff)[_i]), (PG8_LAS unsigned*)(lds + (bufoff) + ldsw + _i * 8192), 16, 0, 0); } while (0)
; #define PG8_LDA(dst, b, h) do { _Pragma("unroll") for (int m = 0; m < 4; ++m) _Pragma("unroll") for (int k = 0; k < 2; ++k) dst[m][k] = *(const PG8_LAS bf16x8*)(lds + PG8_SA(b, h) + aoff + m * 2048 + k * 1024); } while (0)
; #define PG8_LDB(dst, b, h) do { _Pragma("unroll") for (int n = 0; n < 2; ++n) _Pragma("unroll") for (int k = 0; k < 2; ++k) dst[n][k] = *(const PG8_LAS bf16x8*)(lds + PG8_SB(b, h) + boff + n * 2048 + k * 1024); } while (0)
; #define PG8_MMA(ai, bj, At, Bt) do { __builtin_amdgcn_s_setprio(1); _Pragma("unroll") for (int m = 0; m < 4; ++m) _Pragma("unroll") for (int n = 0; n < 2; ++n) _Pragma("unroll") for (int k = 0; k < 2; ++k) \
;         acc[ai][bj][m][n] = __builtin_amdgcn_mfma_f32_16x16x32_bf16(Bt[n][k], At[m][k], acc[ai][bj][m][n], 0, 0, 0); __builtin_amdgcn_s_setprio(0); } while (0)
; #define PG8_WAIT_V(n) asm volatile("s_waitcnt vmcnt(" #n ")" ::: "memory")
; #define PG8_WAIT_L(n) asm volatile("s_waitcnt lgkmcnt(" #n ")" ::: "memory")
; template <class Epi, class Sched, bool ALIGN_EPI = false, bool SP2 = false>
; __device__ __forceinline__ void gemm_phase(PG8_LAS unsigned char* lds, const Gemm g, const Sched& S, const Epi& E) {
;     ...
;             const bool last = (t == nt - 2);
;             const char* a1 = cA + (size_t)(t + 1) * kstep;
;             const char* a2 = last ? nA : cA + (size_t)(t + 2) * kstep; const char* b2 = last ? nB : cB + (size_t)(t + 2) * kstep;
;             const char* a3 = a2 + kstep; const char* b3 = b2 + kstep;
;             if (last && has_next) S.a_ready(nxt);
;             if constexpr (SP2) {
;             PG8_LDB(B0, 0, 0); PG8_LDB(B1, 0, 1); PG8_SCHED; PG8_LDA(At, 0, 0); PG8_STAGE(PG8_SA(1, 1), a1 + hstep, voffA);
;             PG8_WAIT_V(8); PG8_WAIT_L(0); PG8_BAR; PG8_MMA(0, 0, At, B0); PG8_MMA(0, 1, At, B1); PG8_BAR; PG8_SCHED;
;             PG8_LDA(At, 0, 1); PG8_STAGE(PG8_SB(0, 0), b2, voffB); PG8_STAGE(PG8_SB(0, 1), b2 + hstep, voffB); PG8_STAGE(PG8_SA(0, 0), a2, voffA);
;             PG8_WAIT_V(8); PG8_WAIT_L(0); PG8_BAR; PG8_MMA(1, 0, At, B0); PG8_MMA(1, 1, At, B1); PG8_BAR; PG8_SCHED;
.LBB11_228:
	ds_read_b128 v[152:155], v149
	ds_read_b128 v[156:159], v149 offset:1024
	ds_read_b128 v[160:163], v149 offset:2048
	ds_read_b128 v[164:167], v149 offset:3072
	ds_read_b128 v[168:171], v150
	ds_read_b128 v[172:175], v150 offset:1024
	ds_read_b128 v[176:179], v150 offset:2048
	ds_read_b128 v[180:183], v150 offset:3072
	s_add_u32 s30, s28, 0xfff80080
	s_addc_u32 s31, s29, -1
	s_cmp_eq_u32 s61, 28
	s_cselect_b32 s35, s21, s31
	s_cselect_b32 s34, s57, s30
	s_cselect_b32 s31, s19, s60
	s_cselect_b32 s30, s58, s59
	v_lshl_add_u64 v[144:145], s[28:29], 0, v[140:141]
	s_add_i32 m0, s27, 0xc000
	ds_read_b128 v[184:187], v151
	ds_read_b128 v[188:191], v151 offset:1024
	ds_read_b128 v[192:195], v151 offset:2048
	ds_read_b128 v[196:199], v151 offset:3072
	ds_read_b128 v[200:203], v151 offset:4096
	ds_read_b128 v[204:207], v151 offset:5120
	ds_read_b128 v[210:213], v151 offset:6144
	ds_read_b128 v[214:217], v151 offset:7168
	global_load_lds_dwordx4 v[144:145], off
	v_lshl_add_u64 v[144:145], s[28:29], 0, v[142:143]
	s_add_i32 m0, s27, 0xe000
	s_nop 0
	global_load_lds_dwordx4 v[144:145], off
	s_waitcnt vmcnt(8)
	s_waitcnt lgkmcnt(0)
	s_barrier
	s_setprio 1
	s_waitcnt lgkmcnt(0)
	v_mfma_f32_16x16x32_bf16 v[126:129], v[152:155], v[184:187], v[126:129]
	v_mfma_f32_16x16x32_bf16 v[126:129], v[156:159], v[188:191], v[126:129]
	v_mfma_f32_16x16x32_bf16 v[118:121], v[156:159], v[196:199], v[118:121]
	v_mfma_f32_16x16x32_bf16 v[118:121], v[152:155], v[192:195], v[118:121]
	v_mfma_f32_16x16x32_bf16 v[102:105], v[152:155], v[200:203], v[102:105]
	v_mfma_f32_16x16x32_bf16 v[102:105], v[156:159], v[204:207], v[102:105]
	v_mfma_f32_16x16x32_bf16 v[86:89], v[156:159], v[214:217], v[86:89]
	v_mfma_f32_16x16x32_bf16 v[86:89], v[152:155], v[210:213], v[86:89]
	v_mfma_f32_16x16x32_bf16 v[122:125], v[160:163], v[184:187], v[122:125]
	v_mfma_f32_16x16x32_bf16 v[122:125], v[164:167], v[188:191], v[122:125]
	v_mfma_f32_16x16x32_bf16 v[110:113], v[164:167], v[196:199], v[110:113]
	v_mfma_f32_16x16x32_bf16 v[110:113], v[160:163], v[192:195], v[110:113]
	v_mfma_f32_16x16x32_bf16 v[94:97], v[160:163], v[200:203], v[94:97]
	v_mfma_f32_16x16x32_bf16 v[94:97], v[164:167], v[204:207], v[94:97]
	v_mfma_f32_16x16x32_bf16 v[78:81], v[164:167], v[214:217], v[78:81]
	v_mfma_f32_16x16x32_bf16 v[78:81], v[160:163], v[210:213], v[78:81]
	s_setprio 0
	s_setprio 1
	v_mfma_f32_16x16x32_bf16 v[114:117], v[168:171], v[184:187], v[114:117]
	v_mfma_f32_16x16x32_bf16 v[114:117], v[172:175], v[188:191], v[114:117]
	v_mfma_f32_16x16x32_bf16 v[98:101], v[172:175], v[196:199], v[98:101]
	v_mfma_f32_16x16x32_bf16 v[98:101], v[168:171], v[192:195], v[98:101]
	v_mfma_f32_16x16x32_bf16 v[82:85], v[168:171], v[200:203], v[82:85]
	v_mfma_f32_16x16x32_bf16 v[82:85], v[172:175], v[204:207], v[82:85]
	v_mfma_f32_16x16x32_bf16 v[70:73], v[172:175], v[214:217], v[70:73]
	v_mfma_f32_16x16x32_bf16 v[70:73], v[168:171], v[210:213], v[70:73]
	v_mfma_f32_16x16x32_bf16 v[106:109], v[176:179], v[184:187], v[106:109]
	v_mfma_f32_16x16x32_bf16 v[106:109], v[180:183], v[188:191], v[106:109]
	v_mfma_f32_16x16x32_bf16 v[90:93], v[180:183], v[196:199], v[90:93]
	v_mfma_f32_16x16x32_bf16 v[90:93], v[176:179], v[192:195], v[90:93]
	v_mfma_f32_16x16x32_bf16 v[74:77], v[176:179], v[200:203], v[74:77]
	v_mfma_f32_16x16x32_bf16 v[74:77], v[180:183], v[204:207], v[74:77]
	v_mfma_f32_16x16x32_bf16 v[66:69], v[180:183], v[214:217], v[66:69]
	v_mfma_f32_16x16x32_bf16 v[66:69], v[176:179], v[210:213], v[66:69]
	s_setprio 0
	s_barrier
	s_add_i32 s62, s50, s37
	v_lshl_add_u64 v[144:145], s[30:31], 0, v[134:135]
	s_mov_b32 m0, s62
	ds_read_b128 v[184:187], v151 offset:16384
	ds_read_b128 v[188:191], v151 offset:17408
	ds_read_b128 v[192:195], v151 offset:18432
	ds_read_b128 v[196:199], v151 offset:19456
	ds_read_b128 v[200:203], v151 offset:20480
	ds_read_b128 v[204:207], v151 offset:21504
	ds_read_b128 v[210:213], v151 offset:22528
	ds_read_b128 v[214:217], v151 offset:23552
	global_load_lds_dwordx4 v[144:145], off
	s_add_i32 m0, s62, 0x2000
	s_add_u32 s62, s30, 0x80000
	v_lshl_add_u64 v[218:219], s[30:31], 0, v[130:131]
	s_addc_u32 s63, s31, 0
	s_add_i32 s64, s51, s37
	global_load_lds_dwordx4 v[218:219], off
	v_lshl_add_u64 v[220:221], s[62:63], 0, v[134:135]
	s_mov_b32 m0, s64
	v_lshl_add_u64 v[222:223], s[34:35], 0, v[132:133]
	global_load_lds_dwordx4 v[220:221], off
	v_lshl_add_u64 v[220:221], s[62:63], 0, v[130:131]
	s_add_i32 m0, s64, 0x2000
	s_nop 0
	global_load_lds_dwordx4 v[220:221], off
	v_lshl_add_u64 v[220:221], s[34:35], 0, v[136:137]
	s_mov_b32 m0, s27
	s_nop 0
	global_load_lds_dwordx4 v[220:221], off
	s_mov_b32 m0, s39
	s_nop 0
	global_load_lds_dwordx4 v[222:223], off
	s_waitcnt vmcnt(8)
	s_waitcnt lgkmcnt(0)
	s_barrier
; #define PG8_STAGE(bufoff, gbase, voff) do { _Pragma("unroll") for (int _i = 0; _i < 2; ++_i) \
;         __builtin_amdgcn_global_load_lds((const unsigned*)((const char*)(gbase) + (voff)[_i]), (PG8_LAS unsigned*)(lds + (bufoff) + ldsw + _i * 8192), 16, 0, 0); } while (0)
; #define PG8_LDA(dst, b, h) do { _Pragma("unroll") for (int m = 0; m < 4; ++m) _Pragma("unroll") for (int k = 0; k < 2; ++k) dst[m][k] = *(const PG8_LAS bf16x8*)(lds + PG8_SA(b, h) + aoff + m * 2048 + k * 1024); } while (0)
; #define PG8_LDB(dst, b, h) do { _Pragma("unroll") for (int n = 0; n < 2; ++n) _Pragma("unroll") for (int k = 0; k < 2; ++k) dst[n][k] = *(const PG8_LAS bf16x8*)(lds + PG8_SB(b, h) + boff + n * 2048 + k * 1024); } while (0)
; #define PG8_MMA(ai, bj, At, Bt) do { __builtin_amdgcn_s_setprio(1); _Pragma("unroll") for (int m = 0; m < 4; ++m) _Pragma("unroll") for (int n = 0; n < 2; ++n) _Pragma("unroll") for (int k = 0; k < 2; ++k) \
;         acc[ai][bj][m][n] = __builtin_amdgcn_mfma_f32_16x16x32_bf16(Bt[n][k], At[m][k], acc[ai][bj][m][n], 0, 0, 0); __builtin_amdgcn_s_setprio(0); } while (0)
; #define PG8_WAIT_V(n) asm volatile("s_waitcnt vmcnt(" #n ")" ::: "memory")
; #define PG8_WAIT_L(n) asm volatile("s_waitcnt lgkmcnt(" #n ")" ::: "memory")
; #define PG8_BAR __builtin_amdgcn_s_barrier()
; #define PG8_SCHED __builtin_amdgcn_sched_barrier(0)
; template <class Epi, class Sched, bool ALIGN_EPI = false, bool SP2 = false>
; __device__ __forceinline__ void gemm_phase(PG8_LAS unsigned char* lds, const Gemm g, const Sched& S, const Epi& E) {
;     ...
;             PG8_WAIT_V(8); PG8_WAIT_L(0); PG8_BAR; PG8_MMA(1, 0, At, B0); PG8_MMA(1, 1, At, B1); PG8_BAR; PG8_SCHED;
;             PG8_LDB(B0, 1, 0); PG8_LDB(B1, 1, 1); PG8_SCHED; PG8_LDA(At, 1, 0); PG8_STAGE(PG8_SA(0, 1), a2 + hstep, voffA);
;             PG8_WAIT_V(8); PG8_WAIT_L(0); PG8_BAR; PG8_MMA(0, 0, At, B0); PG8_MMA(0, 1, At, B1); PG8_BAR; PG8_SCHED;
	s_setprio 1
	s_waitcnt lgkmcnt(0)
	v_mfma_f32_16x16x32_bf16 v[62:65], v[152:155], v[184:187], v[62:65]
	v_mfma_f32_16x16x32_bf16 v[62:65], v[156:159], v[188:191], v[62:65]
	v_mfma_f32_16x16x32_bf16 v[54:57], v[156:159], v[196:199], v[54:57]
	v_mfma_f32_16x16x32_bf16 v[54:57], v[152:155], v[192:195], v[54:57]
	v_mfma_f32_16x16x32_bf16 v[38:41], v[152:155], v[200:203], v[38:41]
	v_mfma_f32_16x16x32_bf16 v[38:41], v[156:159], v[204:207], v[38:41]
	v_mfma_f32_16x16x32_bf16 v[22:25], v[156:159], v[214:217], v[22:25]
	v_mfma_f32_16x16x32_bf16 v[22:25], v[152:155], v[210:213], v[22:25]
	v_mfma_f32_16x16x32_bf16 v[58:61], v[160:163], v[184:187], v[58:61]
	v_mfma_f32_16x16x32_bf16 v[58:61], v[164:167], v[188:191], v[58:61]
	v_mfma_f32_16x16x32_bf16 v[46:49], v[164:167], v[196:199], v[46:49]
	v_mfma_f32_16x16x32_bf16 v[46:49], v[160:163], v[192:195], v[46:49]
	v_mfma_f32_16x16x32_bf16 v[30:33], v[160:163], v[200:203], v[30:33]
	v_mfma_f32_16x16x32_bf16 v[30:33], v[164:167], v[204:207], v[30:33]
	v_mfma_f32_16x16x32_bf16 v[14:17], v[164:167], v[214:217], v[14:17]
	v_mfma_f32_16x16x32_bf16 v[14:17], v[160:163], v[210:213], v[14:17]
	s_setprio 0
	s_setprio 1
	v_mfma_f32_16x16x32_bf16 v[50:53], v[168:171], v[184:187], v[50:53]
	v_mfma_f32_16x16x32_bf16 v[50:53], v[172:175], v[188:191], v[50:53]
	v_mfma_f32_16x16x32_bf16 v[34:37], v[172:175], v[196:199], v[34:37]
	v_mfma_f32_16x16x32_bf16 v[34:37], v[168:171], v[192:195], v[34:37]
	v_mfma_f32_16x16x32_bf16 v[18:21], v[168:171], v[200:203], v[18:21]
	v_mfma_f32_16x16x32_bf16 v[18:21], v[172:175], v[204:207], v[18:21]
	v_mfma_f32_16x16x32_bf16 v[6:9], v[172:175], v[214:217], v[6:9]
	v_mfma_f32_16x16x32_bf16 v[6:9], v[168:171], v[210:213], v[6:9]
	v_mfma_f32_16x16x32_bf16 v[42:45], v[176:179], v[184:187], v[42:45]
	v_mfma_f32_16x16x32_bf16 v[42:45], v[180:183], v[188:191], v[42:45]
	v_mfma_f32_16x16x32_bf16 v[26:29], v[180:183], v[196:199], v[26:29]
	v_mfma_f32_16x16x32_bf16 v[26:29], v[176:179], v[192:195], v[26:29]
	v_mfma_f32_16x16x32_bf16 v[10:13], v[176:179], v[200:203], v[10:13]
	v_mfma_f32_16x16x32_bf16 v[10:13], v[180:183], v[204:207], v[10:13]
	v_mfma_f32_16x16x32_bf16 v[2:5], v[180:183], v[214:217], v[2:5]
	v_mfma_f32_16x16x32_bf16 v[2:5], v[176:179], v[210:213], v[2:5]
	s_setprio 0
	s_barrier
	s_add_i32 s62, 0, 0x18000
	s_add_i32 s63, 0, 0x1c000
	v_add_u32_e32 v164, s62, v147
	v_add_u32_e32 v180, s63, v147
	ds_read_b128 v[152:155], v164
	ds_read_b128 v[156:159], v164 offset:1024
	ds_read_b128 v[160:163], v164 offset:2048
	ds_read_b128 v[164:167], v164 offset:3072
	ds_read_b128 v[168:171], v180
	ds_read_b128 v[172:175], v180 offset:1024
	ds_read_b128 v[176:179], v180 offset:2048
	ds_read_b128 v[180:183], v180 offset:3072
	s_add_u32 s34, s34, 0x80000
	s_addc_u32 s35, s35, 0
	s_mov_b32 m0, s40
	v_lshl_add_u64 v[224:225], s[34:35], 0, v[136:137]
	ds_read_b128 v[184:187], v151 offset:32768
	ds_read_b128 v[188:191], v151 offset:33792
	ds_read_b128 v[192:195], v151 offset:34816
	ds_read_b128 v[196:199], v151 offset:35840
	ds_read_b128 v[200:203], v151 offset:36864
	ds_read_b128 v[204:207], v151 offset:37888
	ds_read_b128 v[210:213], v151 offset:38912
	ds_read_b128 v[214:217], v151 offset:39936
	global_load_lds_dwordx4 v[224:225], off
	v_lshl_add_u64 v[224:225], s[34:35], 0, v[132:133]
	s_mov_b32 m0, s41
	s_nop 0
	global_load_lds_dwordx4 v[224:225], off
	s_waitcnt vmcnt(8)
	s_waitcnt lgkmcnt(0)
	s_barrier
	s_setprio 1
	s_waitcnt lgkmcnt(0)
	v_mfma_f32_16x16x32_bf16 v[126:129], v[152:155], v[184:187], v[126:129]
	v_mfma_f32_16x16x32_bf16 v[126:129], v[156:159], v[188:191], v[126:129]
	v_mfma_f32_16x16x32_bf16 v[118:121], v[156:159], v[196:199], v[118:121]
	v_mfma_f32_16x16x32_bf16 v[118:121], v[152:155], v[192:195], v[118:121]
	v_mfma_f32_16x16x32_bf16 v[102:105], v[152:155], v[200:203], v[102:105]
	v_mfma_f32_16x16x32_bf16 v[102:105], v[156:159], v[204:207], v[102:105]
	v_mfma_f32_16x16x32_bf16 v[86:89], v[156:159], v[214:217], v[86:89]
	v_mfma_f32_16x16x32_bf16 v[86:89], v[152:155], v[210:213], v[86:89]
	v_mfma_f32_16x16x32_bf16 v[122:125], v[160:163], v[184:187], v[122:125]
	v_mfma_f32_16x16x32_bf16 v[122:125], v[164:167], v[188:191], v[122:125]
	v_mfma_f32_16x16x32_bf16 v[110:113], v[164:167], v[196:199], v[110:113]
	v_mfma_f32_16x16x32_bf16 v[110:113], v[160:163], v[192:195], v[110:113]
	v_mfma_f32_16x16x32_bf16 v[94:97], v[160:163], v[200:203], v[94:97]
	v_mfma_f32_16x16x32_bf16 v[94:97], v[164:167], v[204:207], v[94:97]
	v_mfma_f32_16x16x32_bf16 v[78:81], v[164:167], v[214:217], v[78:81]
	v_mfma_f32_16x16x32_bf16 v[78:81], v[160:163], v[210:213], v[78:81]
	s_setprio 0
	s_setprio 1
	v_mfma_f32_16x16x32_bf16 v[114:117], v[168:171], v[184:187], v[114:117]
	v_mfma_f32_16x16x32_bf16 v[114:117], v[172:175], v[188:191], v[114:117]
	v_mfma_f32_16x16x32_bf16 v[98:101], v[172:175], v[196:199], v[98:101]
	v_mfma_f32_16x16x32_bf16 v[98:101], v[168:171], v[192:195], v[98:101]
	v_mfma_f32_16x16x32_bf16 v[82:85], v[168:171], v[200:203], v[82:85]
	v_mfma_f32_16x16x32_bf16 v[82:85], v[172:175], v[204:207], v[82:85]
	v_mfma_f32_16x16x32_bf16 v[70:73], v[172:175], v[214:217], v[70:73]
	v_mfma_f32_16x16x32_bf16 v[70:73], v[168:171], v[210:213], v[70:73]
	v_mfma_f32_16x16x32_bf16 v[106:109], v[176:179], v[184:187], v[106:109]
	v_mfma_f32_16x16x32_bf16 v[106:109], v[180:183], v[188:191], v[106:109]
	v_mfma_f32_16x16x32_bf16 v[90:93], v[180:183], v[196:199], v[90:93]
	v_mfma_f32_16x16x32_bf16 v[90:93], v[176:179], v[192:195], v[90:93]
	v_mfma_f32_16x16x32_bf16 v[74:77], v[176:179], v[200:203], v[74:77]
	v_mfma_f32_16x16x32_bf16 v[74:77], v[180:183], v[204:207], v[74:77]
	v_mfma_f32_16x16x32_bf16 v[66:69], v[180:183], v[214:217], v[66:69]
	v_mfma_f32_16x16x32_bf16 v[66:69], v[176:179], v[210:213], v[66:69]
	s_setprio 0
	s_barrier
; #define PG8_STAGE(bufoff, gbase, voff) do { _Pragma("unroll") for (int _i = 0; _i < 2; ++_i) \
;         __builtin_amdgcn_global_load_lds((const unsigned*)((const char*)(gbase) + (voff)[_i]), (PG8_LAS unsigned*)(lds + (bufoff) + ldsw + _i * 8192), 16, 0, 0); } while (0)
; #define PG8_LDA(dst, b, h) do { _Pragma("unroll") for (int m = 0; m < 4; ++m) _Pragma("unroll") for (int k = 0; k < 2; ++k) dst[m][k] = *(const PG8_LAS bf16x8*)(lds + PG8_SA(b, h) + aoff + m * 2048 + k * 1024); } while (0)
; #define PG8_MMA(ai, bj, At, Bt) do { __builtin_amdgcn_s_setprio(1); _Pragma("unroll") for (int m = 0; m < 4; ++m) _Pragma("unroll") for (int n = 0; n < 2; ++n) _Pragma("unroll") for (int k = 0; k < 2; ++k) \
;         acc[ai][bj][m][n] = __builtin_amdgcn_mfma_f32_16x16x32_bf16(Bt[n][k], At[m][k], acc[ai][bj][m][n], 0, 0, 0); __builtin_amdgcn_s_setprio(0); } while (0)
; #define PG8_WAIT_V(n) asm volatile("s_waitcnt vmcnt(" #n ")" ::: "memory")
; #define PG8_WAIT_L(n) asm volatile("s_waitcnt lgkmcnt(" #n ")" ::: "memory")
; #define PG8_BAR __builtin_amdgcn_s_barrier()
; #define PG8_SCHED __builtin_amdgcn_sched_barrier(0)
; template <class Epi, class Sched, bool ALIGN_EPI = false, bool SP2 = false>
; __device__ __forceinline__ void gemm_phase(PG8_LAS unsigned char* lds, const Gemm g, const Sched& S, const Epi& E) {
;     ...
;         for (int t = 0; t < nt; t += 2) {
;             const bool last = (t == nt - 2);
;             const char* a1 = cA + (size_t)(t + 1) * kstep;
;             const char* a2 = last ? nA : cA + (size_t)(t + 2) * kstep; const char* b2 = last ? nB : cB + (size_t)(t + 2) * kstep;
;             const char* a3 = a2 + kstep; const char* b3 = b2 + kstep;
;     ...
;             PG8_LDA(At, 1, 1); PG8_STAGE(PG8_SB(1, 0), b3, voffB); PG8_STAGE(PG8_SB(1, 1), b3 + hstep, voffB); PG8_STAGE(PG8_SA(1, 0), a3, voffA);
;             PG8_WAIT_V(8); PG8_WAIT_L(0); PG8_BAR; PG8_MMA(1, 0, At, B0); PG8_MMA(1, 1, At, B1); PG8_BAR; PG8_SCHED;
	s_add_i32 s34, s62, s37
	v_lshl_add_u64 v[144:145], v[144:145], 0, s[6:7]
	s_mov_b32 m0, s34
	ds_read_b128 v[184:187], v151 offset:49152
	ds_read_b128 v[188:191], v151 offset:50176
	ds_read_b128 v[192:195], v151 offset:51200
	ds_read_b128 v[196:199], v151 offset:52224
	ds_read_b128 v[200:203], v151 offset:53248
	ds_read_b128 v[204:207], v151 offset:54272
	ds_read_b128 v[210:213], v151 offset:55296
	ds_read_b128 v[214:217], v151 offset:56320
	global_load_lds_dwordx4 v[144:145], off
	s_add_i32 m0, s34, 0x2000
	s_add_u32 s30, s30, 0x80080
	v_lshl_add_u64 v[144:145], v[218:219], 0, s[6:7]
	s_addc_u32 s31, s31, 0
	s_add_i32 s34, s63, s37
	global_load_lds_dwordx4 v[144:145], off
	v_lshl_add_u64 v[144:145], s[30:31], 0, v[134:135]
	s_mov_b32 m0, s34
	s_nop 0
	global_load_lds_dwordx4 v[144:145], off
	v_lshl_add_u64 v[144:145], s[30:31], 0, v[130:131]
	s_add_i32 m0, s34, 0x2000
	s_nop 0
	global_load_lds_dwordx4 v[144:145], off
	v_lshl_add_u64 v[144:145], v[220:221], 0, s[6:7]
	s_mov_b32 m0, s48
	s_nop 0
	global_load_lds_dwordx4 v[144:145], off
	v_lshl_add_u64 v[144:145], v[222:223], 0, s[6:7]
	s_mov_b32 m0, s49
	s_nop 0
	global_load_lds_dwordx4 v[144:145], off
	s_waitcnt vmcnt(8)
	s_waitcnt lgkmcnt(0)
	s_barrier
	s_setprio 1
	s_waitcnt lgkmcnt(0)
	v_mfma_f32_16x16x32_bf16 v[62:65], v[152:155], v[184:187], v[62:65]
	v_mfma_f32_16x16x32_bf16 v[62:65], v[156:159], v[188:191], v[62:65]
	v_mfma_f32_16x16x32_bf16 v[54:57], v[156:159], v[196:199], v[54:57]
	v_mfma_f32_16x16x32_bf16 v[54:57], v[152:155], v[192:195], v[54:57]
	v_mfma_f32_16x16x32_bf16 v[38:41], v[152:155], v[200:203], v[38:41]
	v_mfma_f32_16x16x32_bf16 v[38:41], v[156:159], v[204:207], v[38:41]
	v_mfma_f32_16x16x32_bf16 v[22:25], v[156:159], v[214:217], v[22:25]
	v_mfma_f32_16x16x32_bf16 v[22:25], v[152:155], v[210:213], v[22:25]
	v_mfma_f32_16x16x32_bf16 v[58:61], v[160:163], v[184:187], v[58:61]
	v_mfma_f32_16x16x32_bf16 v[58:61], v[164:167], v[188:191], v[58:61]
	v_mfma_f32_16x16x32_bf16 v[46:49], v[164:167], v[196:199], v[46:49]
	v_mfma_f32_16x16x32_bf16 v[46:49], v[160:163], v[192:195], v[46:49]
	v_mfma_f32_16x16x32_bf16 v[30:33], v[160:163], v[200:203], v[30:33]
	v_mfma_f32_16x16x32_bf16 v[30:33], v[164:167], v[204:207], v[30:33]
	v_mfma_f32_16x16x32_bf16 v[14:17], v[164:167], v[214:217], v[14:17]
	v_mfma_f32_16x16x32_bf16 v[14:17], v[160:163], v[210:213], v[14:17]
	s_setprio 0
	s_setprio 1
	v_mfma_f32_16x16x32_bf16 v[50:53], v[168:171], v[184:187], v[50:53]
	v_mfma_f32_16x16x32_bf16 v[50:53], v[172:175], v[188:191], v[50:53]
	v_mfma_f32_16x16x32_bf16 v[34:37], v[172:175], v[196:199], v[34:37]
	v_mfma_f32_16x16x32_bf16 v[34:37], v[168:171], v[192:195], v[34:37]
	v_mfma_f32_16x16x32_bf16 v[18:21], v[168:171], v[200:203], v[18:21]
	v_mfma_f32_16x16x32_bf16 v[18:21], v[172:175], v[204:207], v[18:21]
	v_mfma_f32_16x16x32_bf16 v[6:9], v[172:175], v[214:217], v[6:9]
	v_mfma_f32_16x16x32_bf16 v[6:9], v[168:171], v[210:213], v[6:9]
	v_mfma_f32_16x16x32_bf16 v[42:45], v[176:179], v[184:187], v[42:45]
	v_mfma_f32_16x16x32_bf16 v[42:45], v[180:183], v[188:191], v[42:45]
	v_mfma_f32_16x16x32_bf16 v[26:29], v[180:183], v[196:199], v[26:29]
	v_mfma_f32_16x16x32_bf16 v[26:29], v[176:179], v[192:195], v[26:29]
	v_mfma_f32_16x16x32_bf16 v[10:13], v[176:179], v[200:203], v[10:13]
	v_mfma_f32_16x16x32_bf16 v[10:13], v[180:183], v[204:207], v[10:13]
	v_mfma_f32_16x16x32_bf16 v[2:5], v[180:183], v[214:217], v[2:5]
	v_mfma_f32_16x16x32_bf16 v[2:5], v[176:179], v[210:213], v[2:5]
	s_setprio 0
	s_barrier
	s_add_i32 s61, s61, 2
	s_add_u32 s28, s28, 0x100
	s_addc_u32 s29, s29, 0
	s_add_u32 s59, s59, 0x100
	s_addc_u32 s60, s60, 0
	s_cmp_gt_u32 s61, 29
	s_cbranch_scc0 .LBB11_228
	s_and_b64 vcc, exec, s[8:9]
	s_cbranch_vccz .LBB11_231
	s_barrier

; #define PG8_STAGE(bufoff, gbase, voff) do { _Pragma("unroll") for (int _i = 0; _i < 2; ++_i) \
;         __builtin_amdgcn_global_load_lds((const unsigned*)((const char*)(gbase) + (voff)[_i]), (PG8_LAS unsigned*)(lds + (bufoff) + ldsw + _i * 8192), 16, 0, 0); } while (0)
; #define PG8_LDA(dst, b, h) do { _Pragma("unroll") for (int m = 0; m < 4; ++m) _Pragma("unroll") for (int k = 0; k < 2; ++k) dst[m][k] = *(const PG8_LAS bf16x8*)(lds + PG8_SA(b, h) + aoff + m * 2048 + k * 1024); } while (0)
; #define PG8_LDB(dst, b, h) do { _Pragma("unroll") for (int n = 0; n < 2; ++n) _Pragma("unroll") for (int k = 0; k < 2; ++k) dst[n][k] = *(const PG8_LAS bf16x8*)(lds + PG8_SB(b, h) + boff + n * 2048 + k * 1024); } while (0)
; #define PG8_MMA(ai, bj, At, Bt) do { __builtin_amdgcn_s_setprio(1); _Pragma("unroll") for (int m = 0; m < 4; ++m) _Pragma("unroll") for (int n = 0; n < 2; ++n) _Pragma("unroll") for (int k = 0; k < 2; ++k) \
;         acc[ai][bj][m][n] = __builtin_amdgcn_mfma_f32_16x16x32_bf16(Bt[n][k], At[m][k], acc[ai][bj][m][n], 0, 0, 0); __builtin_amdgcn_s_setprio(0); } while (0)
; #define PG8_WAIT_V(n) asm volatile("s_waitcnt vmcnt(" #n ")" ::: "memory")
; #define PG8_WAIT_L(n) asm volatile("s_waitcnt lgkmcnt(" #n ")" ::: "memory")
; template <class Epi, class Sched, bool ALIGN_EPI = false, bool SP2 = false>
; __device__ __forceinline__ void gemm_phase(PG8_LAS unsigned char* lds, const Gemm g, const Sched& S, const Epi& E) {
;     ...
;             const bool last = (t == nt - 2);
;             const char* a1 = cA + (size_t)(t + 1) * kstep;
;             const char* a2 = last ? nA : cA + (size_t)(t + 2) * kstep; const char* b2 = last ? nB : cB + (size_t)(t + 2) * kstep;
;             const char* a3 = a2 + kstep; const char* b3 = b2 + kstep;
;             if (last && has_next) S.a_ready(nxt);
;             if constexpr (SP2) {
;             PG8_LDB(B0, 0, 0); PG8_LDB(B1, 0, 1); PG8_SCHED; PG8_LDA(At, 0, 0); PG8_STAGE(PG8_SA(1, 1), a1 + hstep, voffA);
;             PG8_WAIT_V(8); PG8_WAIT_L(0); PG8_BAR; PG8_MMA(0, 0, At, B0); PG8_MMA(0, 1, At, B1); PG8_BAR; PG8_SCHED;
;             PG8_LDA(At, 0, 1); PG8_STAGE(PG8_SB(0, 0), b2, voffB); PG8_STAGE(PG8_SB(0, 1), b2 + hstep, voffB); PG8_STAGE(PG8_SA(0, 0), a2, voffA);
;             PG8_WAIT_V(8); PG8_WAIT_L(0); PG8_BAR; PG8_MMA(1, 0, At, B0); PG8_MMA(1, 1, At, B1); PG8_BAR; PG8_SCHED;
.LBB11_456:
	s_add_u32 s18, s16, 0xfff80080
	s_addc_u32 s19, s17, -1
	s_add_i32 s49, 0, 0x10000
	s_cmp_eq_u32 s48, 28
	s_cselect_b32 s21, s11, s19
	s_cselect_b32 s20, s44, s18
	v_add_u32_e32 v144, s49, v147
	s_cselect_b32 s19, s9, s47
	s_cselect_b32 s18, s45, s46
	s_add_i32 s52, 0, 0x14000
	ds_read_b128 v[150:153], v144
	ds_read_b128 v[154:157], v144 offset:1024
	ds_read_b128 v[158:161], v144 offset:2048
	ds_read_b128 v[162:165], v144 offset:3072
	v_add_u32_e32 v144, s52, v147
	ds_read_b128 v[166:169], v144
	ds_read_b128 v[170:173], v144 offset:1024
	ds_read_b128 v[174:177], v144 offset:2048
	ds_read_b128 v[178:181], v144 offset:3072
	v_lshl_add_u64 v[144:145], s[16:17], 0, v[140:141]
	s_add_i32 m0, s29, 0xc000
	ds_read_b128 v[198:201], v149
	ds_read_b128 v[202:205], v149 offset:1024
	ds_read_b128 v[220:223], v149 offset:2048
	ds_read_b128 v[224:227], v149 offset:3072
	ds_read_b128 v[228:231], v149 offset:4096
	ds_read_b128 v[232:235], v149 offset:5120
	ds_read_b128 v[236:239], v149 offset:6144
	ds_read_b128 v[240:243], v149 offset:7168
	global_load_lds_dwordx4 v[144:145], off
	v_lshl_add_u64 v[144:145], s[16:17], 0, v[142:143]
	s_add_i32 m0, s29, 0xe000
	s_nop 0
	global_load_lds_dwordx4 v[144:145], off
	s_waitcnt vmcnt(8)
	s_waitcnt lgkmcnt(0)
	s_barrier
	s_setprio 1
	s_waitcnt lgkmcnt(0)
	v_mfma_f32_16x16x32_bf16 v[124:127], v[150:153], v[198:201], v[124:127]
	v_mfma_f32_16x16x32_bf16 v[124:127], v[154:157], v[202:205], v[124:127]
	v_mfma_f32_16x16x32_bf16 v[108:111], v[154:157], v[224:227], v[108:111]
	v_mfma_f32_16x16x32_bf16 v[108:111], v[150:153], v[220:223], v[108:111]
	v_mfma_f32_16x16x32_bf16 v[92:95], v[150:153], v[228:231], v[92:95]
	v_mfma_f32_16x16x32_bf16 v[92:95], v[154:157], v[232:235], v[92:95]
	v_mfma_f32_16x16x32_bf16 v[76:79], v[154:157], v[240:243], v[76:79]
	v_mfma_f32_16x16x32_bf16 v[76:79], v[150:153], v[236:239], v[76:79]
	v_mfma_f32_16x16x32_bf16 v[116:119], v[158:161], v[198:201], v[116:119]
	v_mfma_f32_16x16x32_bf16 v[116:119], v[162:165], v[202:205], v[116:119]
	v_mfma_f32_16x16x32_bf16 v[100:103], v[162:165], v[224:227], v[100:103]
	v_mfma_f32_16x16x32_bf16 v[100:103], v[158:161], v[220:223], v[100:103]
	v_mfma_f32_16x16x32_bf16 v[84:87], v[158:161], v[228:231], v[84:87]
	v_mfma_f32_16x16x32_bf16 v[84:87], v[162:165], v[232:235], v[84:87]
	v_mfma_f32_16x16x32_bf16 v[68:71], v[162:165], v[240:243], v[68:71]
	v_mfma_f32_16x16x32_bf16 v[68:71], v[158:161], v[236:239], v[68:71]
	s_setprio 0
	s_setprio 1
	v_mfma_f32_16x16x32_bf16 v[128:131], v[166:169], v[198:201], v[128:131]
	v_mfma_f32_16x16x32_bf16 v[128:131], v[170:173], v[202:205], v[128:131]
	v_mfma_f32_16x16x32_bf16 v[112:115], v[170:173], v[224:227], v[112:115]
	v_mfma_f32_16x16x32_bf16 v[112:115], v[166:169], v[220:223], v[112:115]
	v_mfma_f32_16x16x32_bf16 v[96:99], v[166:169], v[228:231], v[96:99]
	v_mfma_f32_16x16x32_bf16 v[96:99], v[170:173], v[232:235], v[96:99]
	v_mfma_f32_16x16x32_bf16 v[80:83], v[170:173], v[240:243], v[80:83]
	v_mfma_f32_16x16x32_bf16 v[80:83], v[166:169], v[236:239], v[80:83]
	v_mfma_f32_16x16x32_bf16 v[120:123], v[174:177], v[198:201], v[120:123]
	v_mfma_f32_16x16x32_bf16 v[120:123], v[178:181], v[202:205], v[120:123]
	v_mfma_f32_16x16x32_bf16 v[104:107], v[178:181], v[224:227], v[104:107]
	v_mfma_f32_16x16x32_bf16 v[104:107], v[174:177], v[220:223], v[104:107]
	v_mfma_f32_16x16x32_bf16 v[88:91], v[174:177], v[228:231], v[88:91]
	v_mfma_f32_16x16x32_bf16 v[88:91], v[178:181], v[232:235], v[88:91]
	v_mfma_f32_16x16x32_bf16 v[72:75], v[178:181], v[240:243], v[72:75]
	v_mfma_f32_16x16x32_bf16 v[72:75], v[174:177], v[236:239], v[72:75]
	s_setprio 0
	s_barrier
	s_add_i32 s49, s49, s27
	v_lshl_add_u64 v[144:145], s[18:19], 0, v[2:3]
	s_mov_b32 m0, s49
	ds_read_b128 v[198:201], v149 offset:16384
	ds_read_b128 v[202:205], v149 offset:17408
	ds_read_b128 v[220:223], v149 offset:18432
	ds_read_b128 v[224:227], v149 offset:19456
	ds_read_b128 v[228:231], v149 offset:20480
	ds_read_b128 v[232:235], v149 offset:21504
	ds_read_b128 v[236:239], v149 offset:22528
	ds_read_b128 v[240:243], v149 offset:23552
	global_load_lds_dwordx4 v[144:145], off
	s_add_i32 m0, s49, 0x2000
	s_add_u32 s50, s18, 0x80000
	v_lshl_add_u64 v[206:207], s[18:19], 0, v[132:133]
	s_addc_u32 s51, s19, 0
	s_add_i32 s49, s52, s27
	global_load_lds_dwordx4 v[206:207], off
	v_lshl_add_u64 v[244:245], s[50:51], 0, v[2:3]
	s_mov_b32 m0, s49
	v_lshl_add_u64 v[246:247], s[20:21], 0, v[134:135]
	global_load_lds_dwordx4 v[244:245], off
	v_lshl_add_u64 v[244:245], s[50:51], 0, v[132:133]
	s_add_i32 m0, s49, 0x2000
	s_nop 0
	global_load_lds_dwordx4 v[244:245], off
	v_lshl_add_u64 v[244:245], s[20:21], 0, v[136:137]
	s_mov_b32 m0, s29
	s_nop 0
	global_load_lds_dwordx4 v[244:245], off
	s_mov_b32 m0, s30
	s_nop 0
	global_load_lds_dwordx4 v[246:247], off
	s_waitcnt vmcnt(8)
	s_waitcnt lgkmcnt(0)
	s_barrier
; #define PG8_STAGE(bufoff, gbase, voff) do { _Pragma("unroll") for (int _i = 0; _i < 2; ++_i) \
;         __builtin_amdgcn_global_load_lds((const unsigned*)((const char*)(gbase) + (voff)[_i]), (PG8_LAS unsigned*)(lds + (bufoff) + ldsw + _i * 8192), 16, 0, 0); } while (0)
; #define PG8_LDA(dst, b, h) do { _Pragma("unroll") for (int m = 0; m < 4; ++m) _Pragma("unroll") for (int k = 0; k < 2; ++k) dst[m][k] = *(const PG8_LAS bf16x8*)(lds + PG8_SA(b, h) + aoff + m * 2048 + k * 1024); } while (0)
; #define PG8_LDB(dst, b, h) do { _Pragma("unroll") for (int n = 0; n < 2; ++n) _Pragma("unroll") for (int k = 0; k < 2; ++k) dst[n][k] = *(const PG8_LAS bf16x8*)(lds + PG8_SB(b, h) + boff + n * 2048 + k * 1024); } while (0)
; #define PG8_MMA(ai, bj, At, Bt) do { __builtin_amdgcn_s_setprio(1); _Pragma("unroll") for (int m = 0; m < 4; ++m) _Pragma("unroll") for (int n = 0; n < 2; ++n) _Pragma("unroll") for (int k = 0; k < 2; ++k) \
;         acc[ai][bj][m][n] = __builtin_amdgcn_mfma_f32_16x16x32_bf16(Bt[n][k], At[m][k], acc[ai][bj][m][n], 0, 0, 0); __builtin_amdgcn_s_setprio(0); } while (0)
; #define PG8_WAIT_V(n) asm volatile("s_waitcnt vmcnt(" #n ")" ::: "memory")
; #define PG8_WAIT_L(n) asm volatile("s_waitcnt lgkmcnt(" #n ")" ::: "memory")
; #define PG8_BAR __builtin_amdgcn_s_barrier()
; #define PG8_SCHED __builtin_amdgcn_sched_barrier(0)
; template <class Epi, class Sched, bool ALIGN_EPI = false, bool SP2 = false>
; __device__ __forceinline__ void gemm_phase(PG8_LAS unsigned char* lds, const Gemm g, const Sched& S, const Epi& E) {
;     ...
;             PG8_WAIT_V(8); PG8_WAIT_L(0); PG8_BAR; PG8_MMA(1, 0, At, B0); PG8_MMA(1, 1, At, B1); PG8_BAR; PG8_SCHED;
;             PG8_LDB(B0, 1, 0); PG8_LDB(B1, 1, 1); PG8_SCHED; PG8_LDA(At, 1, 0); PG8_STAGE(PG8_SA(0, 1), a2 + hstep, voffA);
;             PG8_WAIT_V(8); PG8_WAIT_L(0); PG8_BAR; PG8_MMA(0, 0, At, B0); PG8_MMA(0, 1, At, B1); PG8_BAR; PG8_SCHED;
	s_setprio 1
	s_waitcnt lgkmcnt(0)
	v_mfma_f32_16x16x32_bf16 v[60:63], v[150:153], v[198:201], v[60:63]
	v_mfma_f32_16x16x32_bf16 v[60:63], v[154:157], v[202:205], v[60:63]
	v_mfma_f32_16x16x32_bf16 v[44:47], v[154:157], v[224:227], v[44:47]
	v_mfma_f32_16x16x32_bf16 v[44:47], v[150:153], v[220:223], v[44:47]
	v_mfma_f32_16x16x32_bf16 v[28:31], v[150:153], v[228:231], v[28:31]
	v_mfma_f32_16x16x32_bf16 v[28:31], v[154:157], v[232:235], v[28:31]
	v_mfma_f32_16x16x32_bf16 v[12:15], v[154:157], v[240:243], v[12:15]
	v_mfma_f32_16x16x32_bf16 v[12:15], v[150:153], v[236:239], v[12:15]
	v_mfma_f32_16x16x32_bf16 v[52:55], v[158:161], v[198:201], v[52:55]
	v_mfma_f32_16x16x32_bf16 v[52:55], v[162:165], v[202:205], v[52:55]
	v_mfma_f32_16x16x32_bf16 v[36:39], v[162:165], v[224:227], v[36:39]
	v_mfma_f32_16x16x32_bf16 v[36:39], v[158:161], v[220:223], v[36:39]
	v_mfma_f32_16x16x32_bf16 v[20:23], v[158:161], v[228:231], v[20:23]
	v_mfma_f32_16x16x32_bf16 v[20:23], v[162:165], v[232:235], v[20:23]
	v_mfma_f32_16x16x32_bf16 v[4:7], v[162:165], v[240:243], v[4:7]
	v_mfma_f32_16x16x32_bf16 v[4:7], v[158:161], v[236:239], v[4:7]
	s_setprio 0
	s_setprio 1
	v_mfma_f32_16x16x32_bf16 v[64:67], v[166:169], v[198:201], v[64:67]
	v_mfma_f32_16x16x32_bf16 v[64:67], v[170:173], v[202:205], v[64:67]
	v_mfma_f32_16x16x32_bf16 v[48:51], v[170:173], v[224:227], v[48:51]
	v_mfma_f32_16x16x32_bf16 v[48:51], v[166:169], v[220:223], v[48:51]
	v_mfma_f32_16x16x32_bf16 v[32:35], v[166:169], v[228:231], v[32:35]
	v_mfma_f32_16x16x32_bf16 v[32:35], v[170:173], v[232:235], v[32:35]
	v_mfma_f32_16x16x32_bf16 v[16:19], v[170:173], v[240:243], v[16:19]
	v_mfma_f32_16x16x32_bf16 v[16:19], v[166:169], v[236:239], v[16:19]
	v_mfma_f32_16x16x32_bf16 v[56:59], v[174:177], v[198:201], v[56:59]
	v_mfma_f32_16x16x32_bf16 v[56:59], v[178:181], v[202:205], v[56:59]
	v_mfma_f32_16x16x32_bf16 v[40:43], v[178:181], v[224:227], v[40:43]
	v_mfma_f32_16x16x32_bf16 v[40:43], v[174:177], v[220:223], v[40:43]
	v_mfma_f32_16x16x32_bf16 v[24:27], v[174:177], v[228:231], v[24:27]
	v_mfma_f32_16x16x32_bf16 v[24:27], v[178:181], v[232:235], v[24:27]
	v_mfma_f32_16x16x32_bf16 v[8:11], v[178:181], v[240:243], v[8:11]
	v_mfma_f32_16x16x32_bf16 v[8:11], v[174:177], v[236:239], v[8:11]
	s_setprio 0
	s_barrier
	s_add_i32 s49, 0, 0x18000
	s_add_i32 s50, 0, 0x1c000
	v_add_u32_e32 v162, s49, v147
	v_add_u32_e32 v178, s50, v147
	ds_read_b128 v[150:153], v162
	ds_read_b128 v[154:157], v162 offset:1024
	ds_read_b128 v[158:161], v162 offset:2048
	ds_read_b128 v[162:165], v162 offset:3072
	ds_read_b128 v[166:169], v178
	ds_read_b128 v[170:173], v178 offset:1024
	ds_read_b128 v[174:177], v178 offset:2048
	ds_read_b128 v[178:181], v178 offset:3072
	s_add_u32 s20, s20, 0x80000
	s_addc_u32 s21, s21, 0
	s_mov_b32 m0, s33
	v_lshl_add_u64 v[196:197], s[20:21], 0, v[136:137]
	ds_read_b128 v[198:201], v149 offset:32768
	ds_read_b128 v[202:205], v149 offset:33792
	ds_read_b128 v[220:223], v149 offset:34816
	ds_read_b128 v[224:227], v149 offset:35840
	ds_read_b128 v[228:231], v149 offset:36864
	ds_read_b128 v[232:235], v149 offset:37888
	ds_read_b128 v[236:239], v149 offset:38912
	ds_read_b128 v[240:243], v149 offset:39936
	global_load_lds_dwordx4 v[196:197], off
	v_lshl_add_u64 v[196:197], s[20:21], 0, v[134:135]
	s_mov_b32 m0, s38
	s_nop 0
	global_load_lds_dwordx4 v[196:197], off
	s_waitcnt vmcnt(8)
	s_waitcnt lgkmcnt(0)
	s_barrier
	s_setprio 1
	s_waitcnt lgkmcnt(0)
	v_mfma_f32_16x16x32_bf16 v[124:127], v[150:153], v[198:201], v[124:127]
	v_mfma_f32_16x16x32_bf16 v[124:127], v[154:157], v[202:205], v[124:127]
	v_mfma_f32_16x16x32_bf16 v[108:111], v[154:157], v[224:227], v[108:111]
	v_mfma_f32_16x16x32_bf16 v[108:111], v[150:153], v[220:223], v[108:111]
	v_mfma_f32_16x16x32_bf16 v[92:95], v[150:153], v[228:231], v[92:95]
	v_mfma_f32_16x16x32_bf16 v[92:95], v[154:157], v[232:235], v[92:95]
	v_mfma_f32_16x16x32_bf16 v[76:79], v[154:157], v[240:243], v[76:79]
	v_mfma_f32_16x16x32_bf16 v[76:79], v[150:153], v[236:239], v[76:79]
	v_mfma_f32_16x16x32_bf16 v[116:119], v[158:161], v[198:201], v[116:119]
	v_mfma_f32_16x16x32_bf16 v[116:119], v[162:165], v[202:205], v[116:119]
	v_mfma_f32_16x16x32_bf16 v[100:103], v[162:165], v[224:227], v[100:103]
	v_mfma_f32_16x16x32_bf16 v[100:103], v[158:161], v[220:223], v[100:103]
	v_mfma_f32_16x16x32_bf16 v[84:87], v[158:161], v[228:231], v[84:87]
	v_mfma_f32_16x16x32_bf16 v[84:87], v[162:165], v[232:235], v[84:87]
	v_mfma_f32_16x16x32_bf16 v[68:71], v[162:165], v[240:243], v[68:71]
	v_mfma_f32_16x16x32_bf16 v[68:71], v[158:161], v[236:239], v[68:71]
	s_setprio 0
	s_setprio 1
	v_mfma_f32_16x16x32_bf16 v[128:131], v[166:169], v[198:201], v[128:131]
	v_mfma_f32_16x16x32_bf16 v[128:131], v[170:173], v[202:205], v[128:131]
	v_mfma_f32_16x16x32_bf16 v[112:115], v[170:173], v[224:227], v[112:115]
	v_mfma_f32_16x16x32_bf16 v[112:115], v[166:169], v[220:223], v[112:115]
	v_mfma_f32_16x16x32_bf16 v[96:99], v[166:169], v[228:231], v[96:99]
	v_mfma_f32_16x16x32_bf16 v[96:99], v[170:173], v[232:235], v[96:99]
	v_mfma_f32_16x16x32_bf16 v[80:83], v[170:173], v[240:243], v[80:83]
	v_mfma_f32_16x16x32_bf16 v[80:83], v[166:169], v[236:239], v[80:83]
	v_mfma_f32_16x16x32_bf16 v[120:123], v[174:177], v[198:201], v[120:123]
	v_mfma_f32_16x16x32_bf16 v[120:123], v[178:181], v[202:205], v[120:123]
	v_mfma_f32_16x16x32_bf16 v[104:107], v[178:181], v[224:227], v[104:107]
	v_mfma_f32_16x16x32_bf16 v[104:107], v[174:177], v[220:223], v[104:107]
	v_mfma_f32_16x16x32_bf16 v[88:91], v[174:177], v[228:231], v[88:91]
	v_mfma_f32_16x16x32_bf16 v[88:91], v[178:181], v[232:235], v[88:91]
	v_mfma_f32_16x16x32_bf16 v[72:75], v[178:181], v[240:243], v[72:75]
	v_mfma_f32_16x16x32_bf16 v[72:75], v[174:177], v[236:239], v[72:75]
	s_setprio 0
	s_barrier
; #define PG8_STAGE(bufoff, gbase, voff) do { _Pragma("unroll") for (int _i = 0; _i < 2; ++_i) \
;         __builtin_amdgcn_global_load_lds((const unsigned*)((const char*)(gbase) + (voff)[_i]), (PG8_LAS unsigned*)(lds + (bufoff) + ldsw + _i * 8192), 16, 0, 0); } while (0)
; #define PG8_LDA(dst, b, h) do { _Pragma("unroll") for (int m = 0; m < 4; ++m) _Pragma("unroll") for (int k = 0; k < 2; ++k) dst[m][k] = *(const PG8_LAS bf16x8*)(lds + PG8_SA(b, h) + aoff + m * 2048 + k * 1024); } while (0)
; #define PG8_MMA(ai, bj, At, Bt) do { __builtin_amdgcn_s_setprio(1); _Pragma("unroll") for (int m = 0; m < 4; ++m) _Pragma("unroll") for (int n = 0; n < 2; ++n) _Pragma("unroll") for (int k = 0; k < 2; ++k) \
;         acc[ai][bj][m][n] = __builtin_amdgcn_mfma_f32_16x16x32_bf16(Bt[n][k], At[m][k], acc[ai][bj][m][n], 0, 0, 0); __builtin_amdgcn_s_setprio(0); } while (0)
; #define PG8_WAIT_V(n) asm volatile("s_waitcnt vmcnt(" #n ")" ::: "memory")
; #define PG8_WAIT_L(n) asm volatile("s_waitcnt lgkmcnt(" #n ")" ::: "memory")
; #define PG8_BAR __builtin_amdgcn_s_barrier()
; #define PG8_SCHED __builtin_amdgcn_sched_barrier(0)
; template <class Epi, class Sched, bool ALIGN_EPI = false, bool SP2 = false>
; __device__ __forceinline__ void gemm_phase(PG8_LAS unsigned char* lds, const Gemm g, const Sched& S, const Epi& E) {
;     ...
;         for (int t = 0; t < nt; t += 2) {
;             const bool last = (t == nt - 2);
;             const char* a1 = cA + (size_t)(t + 1) * kstep;
;             const char* a2 = last ? nA : cA + (size_t)(t + 2) * kstep; const char* b2 = last ? nB : cB + (size_t)(t + 2) * kstep;
;             const char* a3 = a2 + kstep; const char* b3 = b2 + kstep;
;     ...
;             PG8_LDA(At, 1, 1); PG8_STAGE(PG8_SB(1, 0), b3, voffB); PG8_STAGE(PG8_SB(1, 1), b3 + hstep, voffB); PG8_STAGE(PG8_SA(1, 0), a3, voffA);
;             PG8_WAIT_V(8); PG8_WAIT_L(0); PG8_BAR; PG8_MMA(1, 0, At, B0); PG8_MMA(1, 1, At, B1); PG8_BAR; PG8_SCHED;
	s_add_i32 s20, s49, s27
	v_lshl_add_u64 v[144:145], v[144:145], 0, s[34:35]
	s_mov_b32 m0, s20
	ds_read_b128 v[198:201], v149 offset:49152
	ds_read_b128 v[202:205], v149 offset:50176
	ds_read_b128 v[220:223], v149 offset:51200
	ds_read_b128 v[224:227], v149 offset:52224
	ds_read_b128 v[228:231], v149 offset:53248
	ds_read_b128 v[232:235], v149 offset:54272
	ds_read_b128 v[236:239], v149 offset:55296
	ds_read_b128 v[240:243], v149 offset:56320
	global_load_lds_dwordx4 v[144:145], off
	s_add_i32 m0, s20, 0x2000
	s_add_u32 s18, s18, 0x80080
	v_lshl_add_u64 v[144:145], v[206:207], 0, s[34:35]
	s_addc_u32 s19, s19, 0
	s_add_i32 s20, s50, s27
	global_load_lds_dwordx4 v[144:145], off
	v_lshl_add_u64 v[144:145], s[18:19], 0, v[2:3]
	s_mov_b32 m0, s20
	s_nop 0
	global_load_lds_dwordx4 v[144:145], off
	v_lshl_add_u64 v[144:145], s[18:19], 0, v[132:133]
	s_add_i32 m0, s20, 0x2000
	s_nop 0
	global_load_lds_dwordx4 v[144:145], off
	v_lshl_add_u64 v[144:145], v[244:245], 0, s[34:35]
	s_mov_b32 m0, s39
	s_nop 0
	global_load_lds_dwordx4 v[144:145], off
	v_lshl_add_u64 v[144:145], v[246:247], 0, s[34:35]
	s_mov_b32 m0, s40
	s_nop 0
	global_load_lds_dwordx4 v[144:145], off
	s_waitcnt vmcnt(8)
	s_waitcnt lgkmcnt(0)
	s_barrier
	s_setprio 1
	s_waitcnt lgkmcnt(0)
	v_mfma_f32_16x16x32_bf16 v[60:63], v[150:153], v[198:201], v[60:63]
	v_mfma_f32_16x16x32_bf16 v[60:63], v[154:157], v[202:205], v[60:63]
	v_mfma_f32_16x16x32_bf16 v[44:47], v[154:157], v[224:227], v[44:47]
	v_mfma_f32_16x16x32_bf16 v[44:47], v[150:153], v[220:223], v[44:47]
	v_mfma_f32_16x16x32_bf16 v[28:31], v[150:153], v[228:231], v[28:31]
	v_mfma_f32_16x16x32_bf16 v[28:31], v[154:157], v[232:235], v[28:31]
	v_mfma_f32_16x16x32_bf16 v[12:15], v[154:157], v[240:243], v[12:15]
	v_mfma_f32_16x16x32_bf16 v[12:15], v[150:153], v[236:239], v[12:15]
	v_mfma_f32_16x16x32_bf16 v[52:55], v[158:161], v[198:201], v[52:55]
	v_mfma_f32_16x16x32_bf16 v[52:55], v[162:165], v[202:205], v[52:55]
	v_mfma_f32_16x16x32_bf16 v[36:39], v[162:165], v[224:227], v[36:39]
	v_mfma_f32_16x16x32_bf16 v[36:39], v[158:161], v[220:223], v[36:39]
	v_mfma_f32_16x16x32_bf16 v[20:23], v[158:161], v[228:231], v[20:23]
	v_mfma_f32_16x16x32_bf16 v[20:23], v[162:165], v[232:235], v[20:23]
	v_mfma_f32_16x16x32_bf16 v[4:7], v[162:165], v[240:243], v[4:7]
	v_mfma_f32_16x16x32_bf16 v[4:7], v[158:161], v[236:239], v[4:7]
	s_setprio 0
	s_setprio 1
	v_mfma_f32_16x16x32_bf16 v[64:67], v[166:169], v[198:201], v[64:67]
	v_mfma_f32_16x16x32_bf16 v[64:67], v[170:173], v[202:205], v[64:67]
	v_mfma_f32_16x16x32_bf16 v[48:51], v[170:173], v[224:227], v[48:51]
	v_mfma_f32_16x16x32_bf16 v[48:51], v[166:169], v[220:223], v[48:51]
	v_mfma_f32_16x16x32_bf16 v[32:35], v[166:169], v[228:231], v[32:35]
	v_mfma_f32_16x16x32_bf16 v[32:35], v[170:173], v[232:235], v[32:35]
	v_mfma_f32_16x16x32_bf16 v[16:19], v[170:173], v[240:243], v[16:19]
	v_mfma_f32_16x16x32_bf16 v[16:19], v[166:169], v[236:239], v[16:19]
	v_mfma_f32_16x16x32_bf16 v[56:59], v[174:177], v[198:201], v[56:59]
	v_mfma_f32_16x16x32_bf16 v[56:59], v[178:181], v[202:205], v[56:59]
	v_mfma_f32_16x16x32_bf16 v[40:43], v[178:181], v[224:227], v[40:43]
	v_mfma_f32_16x16x32_bf16 v[40:43], v[174:177], v[220:223], v[40:43]
	v_mfma_f32_16x16x32_bf16 v[24:27], v[174:177], v[228:231], v[24:27]
	v_mfma_f32_16x16x32_bf16 v[24:27], v[178:181], v[232:235], v[24:27]
	v_mfma_f32_16x16x32_bf16 v[8:11], v[178:181], v[240:243], v[8:11]
	v_mfma_f32_16x16x32_bf16 v[8:11], v[174:177], v[236:239], v[8:11]
	s_setprio 0
	s_barrier
	s_add_i32 s48, s48, 2
	s_add_u32 s16, s16, 0x100
	s_addc_u32 s17, s17, 0
	s_add_u32 s46, s46, 0x100
	s_addc_u32 s47, s47, 0
	s_cmp_gt_u32 s48, 29
	s_cbranch_scc0 .LBB11_456
	s_and_b64 vcc, exec, s[6:7]
	s_cbranch_vccz .LBB11_459
	s_barrier

; #define PG8_STAGE(bufoff, gbase, voff) do { _Pragma("unroll") for (int _i = 0; _i < 2; ++_i) \
;         __builtin_amdgcn_global_load_lds((const unsigned*)((const char*)(gbase) + (voff)[_i]), (PG8_LAS unsigned*)(lds + (bufoff) + ldsw + _i * 8192), 16, 0, 0); } while (0)
; #define PG8_LDA(dst, b, h) do { _Pragma("unroll") for (int m = 0; m < 4; ++m) _Pragma("unroll") for (int k = 0; k < 2; ++k) dst[m][k] = *(const PG8_LAS bf16x8*)(lds + PG8_SA(b, h) + aoff + m * 2048 + k * 1024); } while (0)
; #define PG8_LDB(dst, b, h) do { _Pragma("unroll") for (int n = 0; n < 2; ++n) _Pragma("unroll") for (int k = 0; k < 2; ++k) dst[n][k] = *(const PG8_LAS bf16x8*)(lds + PG8_SB(b, h) + boff + n * 2048 + k * 1024); } while (0)
; #define PG8_MMA(ai, bj, At, Bt) do { __builtin_amdgcn_s_setprio(1); _Pragma("unroll") for (int m = 0; m < 4; ++m) _Pragma("unroll") for (int n = 0; n < 2; ++n) _Pragma("unroll") for (int k = 0; k < 2; ++k) \
;         acc[ai][bj][m][n] = __builtin_amdgcn_mfma_f32_16x16x32_bf16(Bt[n][k], At[m][k], acc[ai][bj][m][n], 0, 0, 0); __builtin_amdgcn_s_setprio(0); } while (0)
; #define PG8_WAIT_V(n) asm volatile("s_waitcnt vmcnt(" #n ")" ::: "memory")
; #define PG8_WAIT_L(n) asm volatile("s_waitcnt lgkmcnt(" #n ")" ::: "memory")
; template <class Epi, class Sched, bool ALIGN_EPI = false, bool SP2 = false>
; __device__ __forceinline__ void gemm_phase(PG8_LAS unsigned char* lds, const Gemm g, const Sched& S, const Epi& E) {
;     ...
;             const bool last = (t == nt - 2);
;             const char* a1 = cA + (size_t)(t + 1) * kstep;
;             const char* a2 = last ? nA : cA + (size_t)(t + 2) * kstep; const char* b2 = last ? nB : cB + (size_t)(t + 2) * kstep;
;             const char* a3 = a2 + kstep; const char* b3 = b2 + kstep;
;             if (last && has_next) S.a_ready(nxt);
;             if constexpr (SP2) {
;             PG8_LDB(B0, 0, 0); PG8_LDB(B1, 0, 1); PG8_SCHED; PG8_LDA(At, 0, 0); PG8_STAGE(PG8_SA(1, 1), a1 + hstep, voffA);
;             PG8_WAIT_V(8); PG8_WAIT_L(0); PG8_BAR; PG8_MMA(0, 0, At, B0); PG8_MMA(0, 1, At, B1); PG8_BAR; PG8_SCHED;
;             PG8_LDA(At, 0, 1); PG8_STAGE(PG8_SB(0, 0), b2, voffB); PG8_STAGE(PG8_SB(0, 1), b2 + hstep, voffB); PG8_STAGE(PG8_SA(0, 0), a2, voffA);
;             PG8_WAIT_V(8); PG8_WAIT_L(0); PG8_BAR; PG8_MMA(1, 0, At, B0); PG8_MMA(1, 1, At, B1); PG8_BAR; PG8_SCHED;
.LBB11_638:
	s_add_u32 s20, s18, 0xfff80080
	s_addc_u32 s21, s19, -1
	s_add_i32 s49, 0, 0x10000
	s_cmp_eq_u32 s48, 28
	s_cselect_b32 s23, s13, s21
	s_cselect_b32 s22, s44, s20
	v_add_u32_e32 v144, s49, v147
	s_cselect_b32 s21, s11, s47
	s_cselect_b32 s20, s45, s46
	s_add_i32 s52, 0, 0x14000
	ds_read_b128 v[150:153], v144
	ds_read_b128 v[154:157], v144 offset:1024
	ds_read_b128 v[158:161], v144 offset:2048
	ds_read_b128 v[162:165], v144 offset:3072
	v_add_u32_e32 v144, s52, v147
	ds_read_b128 v[166:169], v144
	ds_read_b128 v[170:173], v144 offset:1024
	ds_read_b128 v[174:177], v144 offset:2048
	ds_read_b128 v[178:181], v144 offset:3072
	v_lshl_add_u64 v[144:145], s[18:19], 0, v[140:141]
	s_add_i32 m0, s33, 0xc000
	ds_read_b128 v[198:201], v149
	ds_read_b128 v[202:205], v149 offset:1024
	ds_read_b128 v[220:223], v149 offset:2048
	ds_read_b128 v[224:227], v149 offset:3072
	ds_read_b128 v[228:231], v149 offset:4096
	ds_read_b128 v[232:235], v149 offset:5120
	ds_read_b128 v[236:239], v149 offset:6144
	ds_read_b128 v[240:243], v149 offset:7168
	global_load_lds_dwordx4 v[144:145], off
	v_lshl_add_u64 v[144:145], s[18:19], 0, v[142:143]
	s_add_i32 m0, s33, 0xe000
	s_nop 0
	global_load_lds_dwordx4 v[144:145], off
	s_waitcnt vmcnt(8)
	s_waitcnt lgkmcnt(0)
	s_barrier
	s_setprio 1
	s_waitcnt lgkmcnt(0)
	v_mfma_f32_16x16x32_bf16 v[128:131], v[150:153], v[198:201], v[128:131]
	v_mfma_f32_16x16x32_bf16 v[128:131], v[154:157], v[202:205], v[128:131]
	v_mfma_f32_16x16x32_bf16 v[120:123], v[154:157], v[224:227], v[120:123]
	v_mfma_f32_16x16x32_bf16 v[120:123], v[150:153], v[220:223], v[120:123]
	v_mfma_f32_16x16x32_bf16 v[104:107], v[150:153], v[228:231], v[104:107]
	v_mfma_f32_16x16x32_bf16 v[104:107], v[154:157], v[232:235], v[104:107]
	v_mfma_f32_16x16x32_bf16 v[88:91], v[154:157], v[240:243], v[88:91]
	v_mfma_f32_16x16x32_bf16 v[88:91], v[150:153], v[236:239], v[88:91]
	v_mfma_f32_16x16x32_bf16 v[124:127], v[158:161], v[198:201], v[124:127]
	v_mfma_f32_16x16x32_bf16 v[124:127], v[162:165], v[202:205], v[124:127]
	v_mfma_f32_16x16x32_bf16 v[112:115], v[162:165], v[224:227], v[112:115]
	v_mfma_f32_16x16x32_bf16 v[112:115], v[158:161], v[220:223], v[112:115]
	v_mfma_f32_16x16x32_bf16 v[96:99], v[158:161], v[228:231], v[96:99]
	v_mfma_f32_16x16x32_bf16 v[96:99], v[162:165], v[232:235], v[96:99]
	v_mfma_f32_16x16x32_bf16 v[80:83], v[162:165], v[240:243], v[80:83]
	v_mfma_f32_16x16x32_bf16 v[80:83], v[158:161], v[236:239], v[80:83]
	s_setprio 0
	s_setprio 1
	v_mfma_f32_16x16x32_bf16 v[116:119], v[166:169], v[198:201], v[116:119]
	v_mfma_f32_16x16x32_bf16 v[116:119], v[170:173], v[202:205], v[116:119]
	v_mfma_f32_16x16x32_bf16 v[100:103], v[170:173], v[224:227], v[100:103]
	v_mfma_f32_16x16x32_bf16 v[100:103], v[166:169], v[220:223], v[100:103]
	v_mfma_f32_16x16x32_bf16 v[84:87], v[166:169], v[228:231], v[84:87]
	v_mfma_f32_16x16x32_bf16 v[84:87], v[170:173], v[232:235], v[84:87]
	v_mfma_f32_16x16x32_bf16 v[72:75], v[170:173], v[240:243], v[72:75]
	v_mfma_f32_16x16x32_bf16 v[72:75], v[166:169], v[236:239], v[72:75]
	v_mfma_f32_16x16x32_bf16 v[108:111], v[174:177], v[198:201], v[108:111]
	v_mfma_f32_16x16x32_bf16 v[108:111], v[178:181], v[202:205], v[108:111]
	v_mfma_f32_16x16x32_bf16 v[92:95], v[178:181], v[224:227], v[92:95]
	v_mfma_f32_16x16x32_bf16 v[92:95], v[174:177], v[220:223], v[92:95]
	v_mfma_f32_16x16x32_bf16 v[76:79], v[174:177], v[228:231], v[76:79]
	v_mfma_f32_16x16x32_bf16 v[76:79], v[178:181], v[232:235], v[76:79]
	v_mfma_f32_16x16x32_bf16 v[68:71], v[178:181], v[240:243], v[68:71]
	v_mfma_f32_16x16x32_bf16 v[68:71], v[174:177], v[236:239], v[68:71]
	s_setprio 0
	s_barrier
	s_add_i32 s49, s49, s30
	v_lshl_add_u64 v[144:145], s[20:21], 0, v[2:3]
	s_mov_b32 m0, s49
	ds_read_b128 v[198:201], v149 offset:16384
	ds_read_b128 v[202:205], v149 offset:17408
	ds_read_b128 v[220:223], v149 offset:18432
	ds_read_b128 v[224:227], v149 offset:19456
	ds_read_b128 v[228:231], v149 offset:20480
	ds_read_b128 v[232:235], v149 offset:21504
	ds_read_b128 v[236:239], v149 offset:22528
	ds_read_b128 v[240:243], v149 offset:23552
	global_load_lds_dwordx4 v[144:145], off
	s_add_i32 m0, s49, 0x2000
	s_add_u32 s50, s20, 0x80000
	v_lshl_add_u64 v[184:185], s[20:21], 0, v[132:133]
	s_addc_u32 s51, s21, 0
	s_add_i32 s49, s52, s30
	global_load_lds_dwordx4 v[184:185], off
	v_lshl_add_u64 v[186:187], s[50:51], 0, v[2:3]
	s_mov_b32 m0, s49
	v_lshl_add_u64 v[196:197], s[22:23], 0, v[134:135]
	global_load_lds_dwordx4 v[186:187], off
	v_lshl_add_u64 v[186:187], s[50:51], 0, v[132:133]
	s_add_i32 m0, s49, 0x2000
	s_nop 0
	global_load_lds_dwordx4 v[186:187], off
	v_lshl_add_u64 v[186:187], s[22:23], 0, v[136:137]
	s_mov_b32 m0, s33
	s_nop 0
	global_load_lds_dwordx4 v[186:187], off
	s_mov_b32 m0, s36
	s_nop 0
	global_load_lds_dwordx4 v[196:197], off
	s_waitcnt vmcnt(8)
	s_waitcnt lgkmcnt(0)
	s_barrier
; #define PG8_STAGE(bufoff, gbase, voff) do { _Pragma("unroll") for (int _i = 0; _i < 2; ++_i) \
;         __builtin_amdgcn_global_load_lds((const unsigned*)((const char*)(gbase) + (voff)[_i]), (PG8_LAS unsigned*)(lds + (bufoff) + ldsw + _i * 8192), 16, 0, 0); } while (0)
; #define PG8_LDA(dst, b, h) do { _Pragma("unroll") for (int m = 0; m < 4; ++m) _Pragma("unroll") for (int k = 0; k < 2; ++k) dst[m][k] = *(const PG8_LAS bf16x8*)(lds + PG8_SA(b, h) + aoff + m * 2048 + k * 1024); } while (0)
; #define PG8_LDB(dst, b, h) do { _Pragma("unroll") for (int n = 0; n < 2; ++n) _Pragma("unroll") for (int k = 0; k < 2; ++k) dst[n][k] = *(const PG8_LAS bf16x8*)(lds + PG8_SB(b, h) + boff + n * 2048 + k * 1024); } while (0)
; #define PG8_MMA(ai, bj, At, Bt) do { __builtin_amdgcn_s_setprio(1); _Pragma("unroll") for (int m = 0; m < 4; ++m) _Pragma("unroll") for (int n = 0; n < 2; ++n) _Pragma("unroll") for (int k = 0; k < 2; ++k) \
;         acc[ai][bj][m][n] = __builtin_amdgcn_mfma_f32_16x16x32_bf16(Bt[n][k], At[m][k], acc[ai][bj][m][n], 0, 0, 0); __builtin_amdgcn_s_setprio(0); } while (0)
; #define PG8_WAIT_V(n) asm volatile("s_waitcnt vmcnt(" #n ")" ::: "memory")
; #define PG8_WAIT_L(n) asm volatile("s_waitcnt lgkmcnt(" #n ")" ::: "memory")
; #define PG8_BAR __builtin_amdgcn_s_barrier()
; #define PG8_SCHED __builtin_amdgcn_sched_barrier(0)
; template <class Epi, class Sched, bool ALIGN_EPI = false, bool SP2 = false>
; __device__ __forceinline__ void gemm_phase(PG8_LAS unsigned char* lds, const Gemm g, const Sched& S, const Epi& E) {
;     ...
;             PG8_WAIT_V(8); PG8_WAIT_L(0); PG8_BAR; PG8_MMA(1, 0, At, B0); PG8_MMA(1, 1, At, B1); PG8_BAR; PG8_SCHED;
;             PG8_LDB(B0, 1, 0); PG8_LDB(B1, 1, 1); PG8_SCHED; PG8_LDA(At, 1, 0); PG8_STAGE(PG8_SA(0, 1), a2 + hstep, voffA);
;             PG8_WAIT_V(8); PG8_WAIT_L(0); PG8_BAR; PG8_MMA(0, 0, At, B0); PG8_MMA(0, 1, At, B1); PG8_BAR; PG8_SCHED;
	s_setprio 1
	s_waitcnt lgkmcnt(0)
	v_mfma_f32_16x16x32_bf16 v[64:67], v[150:153], v[198:201], v[64:67]
	v_mfma_f32_16x16x32_bf16 v[64:67], v[154:157], v[202:205], v[64:67]
	v_mfma_f32_16x16x32_bf16 v[56:59], v[154:157], v[224:227], v[56:59]
	v_mfma_f32_16x16x32_bf16 v[56:59], v[150:153], v[220:223], v[56:59]
	v_mfma_f32_16x16x32_bf16 v[40:43], v[150:153], v[228:231], v[40:43]
	v_mfma_f32_16x16x32_bf16 v[40:43], v[154:157], v[232:235], v[40:43]
	v_mfma_f32_16x16x32_bf16 v[24:27], v[154:157], v[240:243], v[24:27]
	v_mfma_f32_16x16x32_bf16 v[24:27], v[150:153], v[236:239], v[24:27]
	v_mfma_f32_16x16x32_bf16 v[60:63], v[158:161], v[198:201], v[60:63]
	v_mfma_f32_16x16x32_bf16 v[60:63], v[162:165], v[202:205], v[60:63]
	v_mfma_f32_16x16x32_bf16 v[48:51], v[162:165], v[224:227], v[48:51]
	v_mfma_f32_16x16x32_bf16 v[48:51], v[158:161], v[220:223], v[48:51]
	v_mfma_f32_16x16x32_bf16 v[32:35], v[158:161], v[228:231], v[32:35]
	v_mfma_f32_16x16x32_bf16 v[32:35], v[162:165], v[232:235], v[32:35]
	v_mfma_f32_16x16x32_bf16 v[16:19], v[162:165], v[240:243], v[16:19]
	v_mfma_f32_16x16x32_bf16 v[16:19], v[158:161], v[236:239], v[16:19]
	s_setprio 0
	s_setprio 1
	v_mfma_f32_16x16x32_bf16 v[52:55], v[166:169], v[198:201], v[52:55]
	v_mfma_f32_16x16x32_bf16 v[52:55], v[170:173], v[202:205], v[52:55]
	v_mfma_f32_16x16x32_bf16 v[36:39], v[170:173], v[224:227], v[36:39]
	v_mfma_f32_16x16x32_bf16 v[36:39], v[166:169], v[220:223], v[36:39]
	v_mfma_f32_16x16x32_bf16 v[20:23], v[166:169], v[228:231], v[20:23]
	v_mfma_f32_16x16x32_bf16 v[20:23], v[170:173], v[232:235], v[20:23]
	v_mfma_f32_16x16x32_bf16 v[8:11], v[170:173], v[240:243], v[8:11]
	v_mfma_f32_16x16x32_bf16 v[8:11], v[166:169], v[236:239], v[8:11]
	v_mfma_f32_16x16x32_bf16 v[44:47], v[174:177], v[198:201], v[44:47]
	v_mfma_f32_16x16x32_bf16 v[44:47], v[178:181], v[202:205], v[44:47]
	v_mfma_f32_16x16x32_bf16 v[28:31], v[178:181], v[224:227], v[28:31]
	v_mfma_f32_16x16x32_bf16 v[28:31], v[174:177], v[220:223], v[28:31]
	v_mfma_f32_16x16x32_bf16 v[12:15], v[174:177], v[228:231], v[12:15]
	v_mfma_f32_16x16x32_bf16 v[12:15], v[178:181], v[232:235], v[12:15]
	v_mfma_f32_16x16x32_bf16 v[4:7], v[178:181], v[240:243], v[4:7]
	v_mfma_f32_16x16x32_bf16 v[4:7], v[174:177], v[236:239], v[4:7]
	s_setprio 0
	s_barrier
	s_add_i32 s49, 0, 0x18000
	s_add_i32 s50, 0, 0x1c000
	v_add_u32_e32 v162, s49, v147
	v_add_u32_e32 v178, s50, v147
	ds_read_b128 v[150:153], v162
	ds_read_b128 v[154:157], v162 offset:1024
	ds_read_b128 v[158:161], v162 offset:2048
	ds_read_b128 v[162:165], v162 offset:3072
	ds_read_b128 v[166:169], v178
	ds_read_b128 v[170:173], v178 offset:1024
	ds_read_b128 v[174:177], v178 offset:2048
	ds_read_b128 v[178:181], v178 offset:3072
	s_add_u32 s22, s22, 0x80000
	s_addc_u32 s23, s23, 0
	s_mov_b32 m0, s37
	v_lshl_add_u64 v[206:207], s[22:23], 0, v[136:137]
	ds_read_b128 v[198:201], v149 offset:32768
	ds_read_b128 v[202:205], v149 offset:33792
	ds_read_b128 v[220:223], v149 offset:34816
	ds_read_b128 v[224:227], v149 offset:35840
	ds_read_b128 v[228:231], v149 offset:36864
	ds_read_b128 v[232:235], v149 offset:37888
	ds_read_b128 v[236:239], v149 offset:38912
	ds_read_b128 v[240:243], v149 offset:39936
	global_load_lds_dwordx4 v[206:207], off
	v_lshl_add_u64 v[206:207], s[22:23], 0, v[134:135]
	s_mov_b32 m0, s38
	s_nop 0
	global_load_lds_dwordx4 v[206:207], off
	s_waitcnt vmcnt(8)
	s_waitcnt lgkmcnt(0)
	s_barrier
	s_setprio 1
	s_waitcnt lgkmcnt(0)
	v_mfma_f32_16x16x32_bf16 v[128:131], v[150:153], v[198:201], v[128:131]
	v_mfma_f32_16x16x32_bf16 v[128:131], v[154:157], v[202:205], v[128:131]
	v_mfma_f32_16x16x32_bf16 v[120:123], v[154:157], v[224:227], v[120:123]
	v_mfma_f32_16x16x32_bf16 v[120:123], v[150:153], v[220:223], v[120:123]
	v_mfma_f32_16x16x32_bf16 v[104:107], v[150:153], v[228:231], v[104:107]
	v_mfma_f32_16x16x32_bf16 v[104:107], v[154:157], v[232:235], v[104:107]
	v_mfma_f32_16x16x32_bf16 v[88:91], v[154:157], v[240:243], v[88:91]
	v_mfma_f32_16x16x32_bf16 v[88:91], v[150:153], v[236:239], v[88:91]
	v_mfma_f32_16x16x32_bf16 v[124:127], v[158:161], v[198:201], v[124:127]
	v_mfma_f32_16x16x32_bf16 v[124:127], v[162:165], v[202:205], v[124:127]
	v_mfma_f32_16x16x32_bf16 v[112:115], v[162:165], v[224:227], v[112:115]
	v_mfma_f32_16x16x32_bf16 v[112:115], v[158:161], v[220:223], v[112:115]
	v_mfma_f32_16x16x32_bf16 v[96:99], v[158:161], v[228:231], v[96:99]
	v_mfma_f32_16x16x32_bf16 v[96:99], v[162:165], v[232:235], v[96:99]
	v_mfma_f32_16x16x32_bf16 v[80:83], v[162:165], v[240:243], v[80:83]
	v_mfma_f32_16x16x32_bf16 v[80:83], v[158:161], v[236:239], v[80:83]
	s_setprio 0
	s_setprio 1
	v_mfma_f32_16x16x32_bf16 v[116:119], v[166:169], v[198:201], v[116:119]
	v_mfma_f32_16x16x32_bf16 v[116:119], v[170:173], v[202:205], v[116:119]
	v_mfma_f32_16x16x32_bf16 v[100:103], v[170:173], v[224:227], v[100:103]
	v_mfma_f32_16x16x32_bf16 v[100:103], v[166:169], v[220:223], v[100:103]
	v_mfma_f32_16x16x32_bf16 v[84:87], v[166:169], v[228:231], v[84:87]
	v_mfma_f32_16x16x32_bf16 v[84:87], v[170:173], v[232:235], v[84:87]
	v_mfma_f32_16x16x32_bf16 v[72:75], v[170:173], v[240:243], v[72:75]
	v_mfma_f32_16x16x32_bf16 v[72:75], v[166:169], v[236:239], v[72:75]
	v_mfma_f32_16x16x32_bf16 v[108:111], v[174:177], v[198:201], v[108:111]
	v_mfma_f32_16x16x32_bf16 v[108:111], v[178:181], v[202:205], v[108:111]
	v_mfma_f32_16x16x32_bf16 v[92:95], v[178:181], v[224:227], v[92:95]
	v_mfma_f32_16x16x32_bf16 v[92:95], v[174:177], v[220:223], v[92:95]
	v_mfma_f32_16x16x32_bf16 v[76:79], v[174:177], v[228:231], v[76:79]
	v_mfma_f32_16x16x32_bf16 v[76:79], v[178:181], v[232:235], v[76:79]
	v_mfma_f32_16x16x32_bf16 v[68:71], v[178:181], v[240:243], v[68:71]
	v_mfma_f32_16x16x32_bf16 v[68:71], v[174:177], v[236:239], v[68:71]
	s_setprio 0
	s_barrier
; #define PG8_STAGE(bufoff, gbase, voff) do { _Pragma("unroll") for (int _i = 0; _i < 2; ++_i) \
;         __builtin_amdgcn_global_load_lds((const unsigned*)((const char*)(gbase) + (voff)[_i]), (PG8_LAS unsigned*)(lds + (bufoff) + ldsw + _i * 8192), 16, 0, 0); } while (0)
; #define PG8_LDA(dst, b, h) do { _Pragma("unroll") for (int m = 0; m < 4; ++m) _Pragma("unroll") for (int k = 0; k < 2; ++k) dst[m][k] = *(const PG8_LAS bf16x8*)(lds + PG8_SA(b, h) + aoff + m * 2048 + k * 1024); } while (0)
; #define PG8_MMA(ai, bj, At, Bt) do { __builtin_amdgcn_s_setprio(1); _Pragma("unroll") for (int m = 0; m < 4; ++m) _Pragma("unroll") for (int n = 0; n < 2; ++n) _Pragma("unroll") for (int k = 0; k < 2; ++k) \
;         acc[ai][bj][m][n] = __builtin_amdgcn_mfma_f32_16x16x32_bf16(Bt[n][k], At[m][k], acc[ai][bj][m][n], 0, 0, 0); __builtin_amdgcn_s_setprio(0); } while (0)
; #define PG8_WAIT_V(n) asm volatile("s_waitcnt vmcnt(" #n ")" ::: "memory")
; #define PG8_WAIT_L(n) asm volatile("s_waitcnt lgkmcnt(" #n ")" ::: "memory")
; #define PG8_BAR __builtin_amdgcn_s_barrier()
; #define PG8_SCHED __builtin_amdgcn_sched_barrier(0)
; template <class Epi, class Sched, bool ALIGN_EPI = false, bool SP2 = false>
; __device__ __forceinline__ void gemm_phase(PG8_LAS unsigned char* lds, const Gemm g, const Sched& S, const Epi& E) {
;     ...
;         for (int t = 0; t < nt; t += 2) {
;             const bool last = (t == nt - 2);
;             const char* a1 = cA + (size_t)(t + 1) * kstep;
;             const char* a2 = last ? nA : cA + (size_t)(t + 2) * kstep; const char* b2 = last ? nB : cB + (size_t)(t + 2) * kstep;
;             const char* a3 = a2 + kstep; const char* b3 = b2 + kstep;
;     ...
;             PG8_LDA(At, 1, 1); PG8_STAGE(PG8_SB(1, 0), b3, voffB); PG8_STAGE(PG8_SB(1, 1), b3 + hstep, voffB); PG8_STAGE(PG8_SA(1, 0), a3, voffA);
;             PG8_WAIT_V(8); PG8_WAIT_L(0); PG8_BAR; PG8_MMA(1, 0, At, B0); PG8_MMA(1, 1, At, B1); PG8_BAR; PG8_SCHED;
	s_add_i32 s22, s49, s30
	v_lshl_add_u64 v[144:145], v[144:145], 0, s[34:35]
	s_mov_b32 m0, s22
	ds_read_b128 v[198:201], v149 offset:49152
	ds_read_b128 v[202:205], v149 offset:50176
	ds_read_b128 v[220:223], v149 offset:51200
	ds_read_b128 v[224:227], v149 offset:52224
	ds_read_b128 v[228:231], v149 offset:53248
	ds_read_b128 v[232:235], v149 offset:54272
	ds_read_b128 v[236:239], v149 offset:55296
	ds_read_b128 v[240:243], v149 offset:56320
	global_load_lds_dwordx4 v[144:145], off
	s_add_i32 m0, s22, 0x2000
	s_add_u32 s20, s20, 0x80080
	v_lshl_add_u64 v[144:145], v[184:185], 0, s[34:35]
	s_addc_u32 s21, s21, 0
	s_add_i32 s22, s50, s30
	global_load_lds_dwordx4 v[144:145], off
	v_lshl_add_u64 v[144:145], s[20:21], 0, v[2:3]
	s_mov_b32 m0, s22
	s_nop 0
	global_load_lds_dwordx4 v[144:145], off
	v_lshl_add_u64 v[144:145], s[20:21], 0, v[132:133]
	s_add_i32 m0, s22, 0x2000
	s_nop 0
	global_load_lds_dwordx4 v[144:145], off
	v_lshl_add_u64 v[144:145], v[186:187], 0, s[34:35]
	s_mov_b32 m0, s39
	s_nop 0
	global_load_lds_dwordx4 v[144:145], off
	v_lshl_add_u64 v[144:145], v[196:197], 0, s[34:35]
	s_mov_b32 m0, s40
	s_nop 0
	global_load_lds_dwordx4 v[144:145], off
	s_waitcnt vmcnt(8)
	s_waitcnt lgkmcnt(0)
	s_barrier
	s_setprio 1
	s_waitcnt lgkmcnt(0)
	v_mfma_f32_16x16x32_bf16 v[64:67], v[150:153], v[198:201], v[64:67]
	v_mfma_f32_16x16x32_bf16 v[64:67], v[154:157], v[202:205], v[64:67]
	v_mfma_f32_16x16x32_bf16 v[56:59], v[154:157], v[224:227], v[56:59]
	v_mfma_f32_16x16x32_bf16 v[56:59], v[150:153], v[220:223], v[56:59]
	v_mfma_f32_16x16x32_bf16 v[40:43], v[150:153], v[228:231], v[40:43]
	v_mfma_f32_16x16x32_bf16 v[40:43], v[154:157], v[232:235], v[40:43]
	v_mfma_f32_16x16x32_bf16 v[24:27], v[154:157], v[240:243], v[24:27]
	v_mfma_f32_16x16x32_bf16 v[24:27], v[150:153], v[236:239], v[24:27]
	v_mfma_f32_16x16x32_bf16 v[60:63], v[158:161], v[198:201], v[60:63]
	v_mfma_f32_16x16x32_bf16 v[60:63], v[162:165], v[202:205], v[60:63]
	v_mfma_f32_16x16x32_bf16 v[48:51], v[162:165], v[224:227], v[48:51]
	v_mfma_f32_16x16x32_bf16 v[48:51], v[158:161], v[220:223], v[48:51]
	v_mfma_f32_16x16x32_bf16 v[32:35], v[158:161], v[228:231], v[32:35]
	v_mfma_f32_16x16x32_bf16 v[32:35], v[162:165], v[232:235], v[32:35]
	v_mfma_f32_16x16x32_bf16 v[16:19], v[162:165], v[240:243], v[16:19]
	v_mfma_f32_16x16x32_bf16 v[16:19], v[158:161], v[236:239], v[16:19]
	s_setprio 0
	s_setprio 1
	v_mfma_f32_16x16x32_bf16 v[52:55], v[166:169], v[198:201], v[52:55]
	v_mfma_f32_16x16x32_bf16 v[52:55], v[170:173], v[202:205], v[52:55]
	v_mfma_f32_16x16x32_bf16 v[36:39], v[170:173], v[224:227], v[36:39]
	v_mfma_f32_16x16x32_bf16 v[36:39], v[166:169], v[220:223], v[36:39]
	v_mfma_f32_16x16x32_bf16 v[20:23], v[166:169], v[228:231], v[20:23]
	v_mfma_f32_16x16x32_bf16 v[20:23], v[170:173], v[232:235], v[20:23]
	v_mfma_f32_16x16x32_bf16 v[8:11], v[170:173], v[240:243], v[8:11]
	v_mfma_f32_16x16x32_bf16 v[8:11], v[166:169], v[236:239], v[8:11]
	v_mfma_f32_16x16x32_bf16 v[44:47], v[174:177], v[198:201], v[44:47]
	v_mfma_f32_16x16x32_bf16 v[44:47], v[178:181], v[202:205], v[44:47]
	v_mfma_f32_16x16x32_bf16 v[28:31], v[178:181], v[224:227], v[28:31]
	v_mfma_f32_16x16x32_bf16 v[28:31], v[174:177], v[220:223], v[28:31]
	v_mfma_f32_16x16x32_bf16 v[12:15], v[174:177], v[228:231], v[12:15]
	v_mfma_f32_16x16x32_bf16 v[12:15], v[178:181], v[232:235], v[12:15]
	v_mfma_f32_16x16x32_bf16 v[4:7], v[178:181], v[240:243], v[4:7]
	v_mfma_f32_16x16x32_bf16 v[4:7], v[174:177], v[236:239], v[4:7]
	s_setprio 0
	s_barrier
	s_add_i32 s48, s48, 2
	s_add_u32 s18, s18, 0x100
	s_addc_u32 s19, s19, 0
	s_add_u32 s46, s46, 0x100
	s_addc_u32 s47, s47, 0
	s_cmp_gt_u32 s48, 29
	s_cbranch_scc0 .LBB11_638
	s_and_b64 vcc, exec, s[4:5]
	s_cbranch_vccz .LBB11_641
	s_barrier

; #define PG8_STAGE(bufoff, gbase, voff) do { _Pragma("unroll") for (int _i = 0; _i < 2; ++_i) \
;         __builtin_amdgcn_global_load_lds((const unsigned*)((const char*)(gbase) + (voff)[_i]), (PG8_LAS unsigned*)(lds + (bufoff) + ldsw + _i * 8192), 16, 0, 0); } while (0)
; #define PG8_LDA(dst, b, h) do { _Pragma("unroll") for (int m = 0; m < 4; ++m) _Pragma("unroll") for (int k = 0; k < 2; ++k) dst[m][k] = *(const PG8_LAS bf16x8*)(lds + PG8_SA(b, h) + aoff + m * 2048 + k * 1024); } while (0)
; #define PG8_LDB(dst, b, h) do { _Pragma("unroll") for (int n = 0; n < 2; ++n) _Pragma("unroll") for (int k = 0; k < 2; ++k) dst[n][k] = *(const PG8_LAS bf16x8*)(lds + PG8_SB(b, h) + boff + n * 2048 + k * 1024); } while (0)
; #define PG8_MMA(ai, bj, At, Bt) do { __builtin_amdgcn_s_setprio(1); _Pragma("unroll") for (int m = 0; m < 4; ++m) _Pragma("unroll") for (int n = 0; n < 2; ++n) _Pragma("unroll") for (int k = 0; k < 2; ++k) \
;         acc[ai][bj][m][n] = __builtin_amdgcn_mfma_f32_16x16x32_bf16(Bt[n][k], At[m][k], acc[ai][bj][m][n], 0, 0, 0); __builtin_amdgcn_s_setprio(0); } while (0)
; #define PG8_WAIT_V(n) asm volatile("s_waitcnt vmcnt(" #n ")" ::: "memory")
; #define PG8_WAIT_L(n) asm volatile("s_waitcnt lgkmcnt(" #n ")" ::: "memory")
; template <class Epi, class Sched, bool ALIGN_EPI = false, bool SP2 = false>
; __device__ __forceinline__ void gemm_phase(PG8_LAS unsigned char* lds, const Gemm g, const Sched& S, const Epi& E) {
;     ...
;             const bool last = (t == nt - 2);
;             const char* a1 = cA + (size_t)(t + 1) * kstep;
;             const char* a2 = last ? nA : cA + (size_t)(t + 2) * kstep; const char* b2 = last ? nB : cB + (size_t)(t + 2) * kstep;
;             const char* a3 = a2 + kstep; const char* b3 = b2 + kstep;
;             if (last && has_next) S.a_ready(nxt);
;             if constexpr (SP2) {
;             PG8_LDB(B0, 0, 0); PG8_LDB(B1, 0, 1); PG8_SCHED; PG8_LDA(At, 0, 0); PG8_STAGE(PG8_SA(1, 1), a1 + hstep, voffA);
;             PG8_WAIT_V(8); PG8_WAIT_L(0); PG8_BAR; PG8_MMA(0, 0, At, B0); PG8_MMA(0, 1, At, B1); PG8_BAR; PG8_SCHED;
;             PG8_LDA(At, 0, 1); PG8_STAGE(PG8_SB(0, 0), b2, voffB); PG8_STAGE(PG8_SB(0, 1), b2 + hstep, voffB); PG8_STAGE(PG8_SA(0, 0), a2, voffA);
;             PG8_WAIT_V(8); PG8_WAIT_L(0); PG8_BAR; PG8_MMA(1, 0, At, B0); PG8_MMA(1, 1, At, B1); PG8_BAR; PG8_SCHED;
.LBB11_913:
	s_add_u32 s16, s14, 0xfff80080
	s_addc_u32 s17, s15, -1
	s_add_i32 s44, 0, 0x10000
	s_cmp_eq_u32 s43, 28
	s_cselect_b32 s19, s9, s17
	s_cselect_b32 s18, s37, s16
	v_add_u32_e32 v144, s44, v146
	s_cselect_b32 s17, s7, s42
	s_cselect_b32 s16, s40, s41
	s_add_i32 s46, 0, 0x14000
	ds_read_b128 v[150:153], v144
	ds_read_b128 v[154:157], v144 offset:1024
	ds_read_b128 v[158:161], v144 offset:2048
	ds_read_b128 v[162:165], v144 offset:3072
	v_add_u32_e32 v144, s46, v146
	ds_read_b128 v[166:169], v144
	ds_read_b128 v[170:173], v144 offset:1024
	ds_read_b128 v[174:177], v144 offset:2048
	ds_read_b128 v[178:181], v144 offset:3072
	v_lshl_add_u64 v[144:145], s[14:15], 0, v[140:141]
	s_add_i32 m0, s24, 0xc000
	ds_read_b128 v[198:201], v148
	ds_read_b128 v[202:205], v148 offset:1024
	ds_read_b128 v[220:223], v148 offset:2048
	ds_read_b128 v[224:227], v148 offset:3072
	ds_read_b128 v[228:231], v148 offset:4096
	ds_read_b128 v[232:235], v148 offset:5120
	ds_read_b128 v[236:239], v148 offset:6144
	ds_read_b128 v[240:243], v148 offset:7168
	global_load_lds_dwordx4 v[144:145], off
	v_lshl_add_u64 v[144:145], s[14:15], 0, v[142:143]
	s_add_i32 m0, s24, 0xe000
	s_nop 0
	global_load_lds_dwordx4 v[144:145], off
	s_waitcnt vmcnt(8)
	s_waitcnt lgkmcnt(0)
	s_barrier
	s_setprio 1
	s_waitcnt lgkmcnt(0)
	v_mfma_f32_16x16x32_bf16 v[128:131], v[150:153], v[198:201], v[128:131]
	v_mfma_f32_16x16x32_bf16 v[128:131], v[154:157], v[202:205], v[128:131]
	v_mfma_f32_16x16x32_bf16 v[120:123], v[154:157], v[224:227], v[120:123]
	v_mfma_f32_16x16x32_bf16 v[120:123], v[150:153], v[220:223], v[120:123]
	v_mfma_f32_16x16x32_bf16 v[104:107], v[150:153], v[228:231], v[104:107]
	v_mfma_f32_16x16x32_bf16 v[104:107], v[154:157], v[232:235], v[104:107]
	v_mfma_f32_16x16x32_bf16 v[88:91], v[154:157], v[240:243], v[88:91]
	v_mfma_f32_16x16x32_bf16 v[88:91], v[150:153], v[236:239], v[88:91]
	v_mfma_f32_16x16x32_bf16 v[124:127], v[158:161], v[198:201], v[124:127]
	v_mfma_f32_16x16x32_bf16 v[124:127], v[162:165], v[202:205], v[124:127]
	v_mfma_f32_16x16x32_bf16 v[112:115], v[162:165], v[224:227], v[112:115]
	v_mfma_f32_16x16x32_bf16 v[112:115], v[158:161], v[220:223], v[112:115]
	v_mfma_f32_16x16x32_bf16 v[96:99], v[158:161], v[228:231], v[96:99]
	v_mfma_f32_16x16x32_bf16 v[96:99], v[162:165], v[232:235], v[96:99]
	v_mfma_f32_16x16x32_bf16 v[80:83], v[162:165], v[240:243], v[80:83]
	v_mfma_f32_16x16x32_bf16 v[80:83], v[158:161], v[236:239], v[80:83]
	s_setprio 0
	s_setprio 1
	v_mfma_f32_16x16x32_bf16 v[116:119], v[166:169], v[198:201], v[116:119]
	v_mfma_f32_16x16x32_bf16 v[116:119], v[170:173], v[202:205], v[116:119]
	v_mfma_f32_16x16x32_bf16 v[100:103], v[170:173], v[224:227], v[100:103]
	v_mfma_f32_16x16x32_bf16 v[100:103], v[166:169], v[220:223], v[100:103]
	v_mfma_f32_16x16x32_bf16 v[84:87], v[166:169], v[228:231], v[84:87]
	v_mfma_f32_16x16x32_bf16 v[84:87], v[170:173], v[232:235], v[84:87]
	v_mfma_f32_16x16x32_bf16 v[72:75], v[170:173], v[240:243], v[72:75]
	v_mfma_f32_16x16x32_bf16 v[72:75], v[166:169], v[236:239], v[72:75]
	v_mfma_f32_16x16x32_bf16 v[108:111], v[174:177], v[198:201], v[108:111]
	v_mfma_f32_16x16x32_bf16 v[108:111], v[178:181], v[202:205], v[108:111]
	v_mfma_f32_16x16x32_bf16 v[92:95], v[178:181], v[224:227], v[92:95]
	v_mfma_f32_16x16x32_bf16 v[92:95], v[174:177], v[220:223], v[92:95]
	v_mfma_f32_16x16x32_bf16 v[76:79], v[174:177], v[228:231], v[76:79]
	v_mfma_f32_16x16x32_bf16 v[76:79], v[178:181], v[232:235], v[76:79]
	v_mfma_f32_16x16x32_bf16 v[68:71], v[178:181], v[240:243], v[68:71]
	v_mfma_f32_16x16x32_bf16 v[68:71], v[174:177], v[236:239], v[68:71]
	s_setprio 0
	s_barrier
	s_add_i32 s44, s44, s23
	v_lshl_add_u64 v[144:145], s[16:17], 0, v[2:3]
	s_mov_b32 m0, s44
	ds_read_b128 v[198:201], v148 offset:16384
	ds_read_b128 v[202:205], v148 offset:17408
	ds_read_b128 v[220:223], v148 offset:18432
	ds_read_b128 v[224:227], v148 offset:19456
	ds_read_b128 v[228:231], v148 offset:20480
	ds_read_b128 v[232:235], v148 offset:21504
	ds_read_b128 v[236:239], v148 offset:22528
	ds_read_b128 v[240:243], v148 offset:23552
	global_load_lds_dwordx4 v[144:145], off
	s_add_i32 m0, s44, 0x2000
	s_add_u32 s44, s16, 0x80000
	v_lshl_add_u64 v[184:185], s[16:17], 0, v[132:133]
	s_addc_u32 s45, s17, 0
	s_add_i32 s46, s46, s23
	global_load_lds_dwordx4 v[184:185], off
	v_lshl_add_u64 v[186:187], s[44:45], 0, v[2:3]
	s_mov_b32 m0, s46
	v_lshl_add_u64 v[196:197], s[18:19], 0, v[134:135]
	global_load_lds_dwordx4 v[186:187], off
	v_lshl_add_u64 v[186:187], s[44:45], 0, v[132:133]
	s_add_i32 m0, s46, 0x2000
	s_nop 0
	global_load_lds_dwordx4 v[186:187], off
	v_lshl_add_u64 v[186:187], s[18:19], 0, v[136:137]
	s_mov_b32 m0, s24
	s_nop 0
	global_load_lds_dwordx4 v[186:187], off
	s_mov_b32 m0, s25
	s_nop 0
	global_load_lds_dwordx4 v[196:197], off
	s_waitcnt vmcnt(8)
	s_waitcnt lgkmcnt(0)
	s_barrier
; #define PG8_STAGE(bufoff, gbase, voff) do { _Pragma("unroll") for (int _i = 0; _i < 2; ++_i) \
;         __builtin_amdgcn_global_load_lds((const unsigned*)((const char*)(gbase) + (voff)[_i]), (PG8_LAS unsigned*)(lds + (bufoff) + ldsw + _i * 8192), 16, 0, 0); } while (0)
; #define PG8_LDA(dst, b, h) do { _Pragma("unroll") for (int m = 0; m < 4; ++m) _Pragma("unroll") for (int k = 0; k < 2; ++k) dst[m][k] = *(const PG8_LAS bf16x8*)(lds + PG8_SA(b, h) + aoff + m * 2048 + k * 1024); } while (0)
; #define PG8_LDB(dst, b, h) do { _Pragma("unroll") for (int n = 0; n < 2; ++n) _Pragma("unroll") for (int k = 0; k < 2; ++k) dst[n][k] = *(const PG8_LAS bf16x8*)(lds + PG8_SB(b, h) + boff + n * 2048 + k * 1024); } while (0)
; #define PG8_MMA(ai, bj, At, Bt) do { __builtin_amdgcn_s_setprio(1); _Pragma("unroll") for (int m = 0; m < 4; ++m) _Pragma("unroll") for (int n = 0; n < 2; ++n) _Pragma("unroll") for (int k = 0; k < 2; ++k) \
;         acc[ai][bj][m][n] = __builtin_amdgcn_mfma_f32_16x16x32_bf16(Bt[n][k], At[m][k], acc[ai][bj][m][n], 0, 0, 0); __builtin_amdgcn_s_setprio(0); } while (0)
; #define PG8_WAIT_V(n) asm volatile("s_waitcnt vmcnt(" #n ")" ::: "memory")
; #define PG8_WAIT_L(n) asm volatile("s_waitcnt lgkmcnt(" #n ")" ::: "memory")
; #define PG8_BAR __builtin_amdgcn_s_barrier()
; #define PG8_SCHED __builtin_amdgcn_sched_barrier(0)
; template <class Epi, class Sched, bool ALIGN_EPI = false, bool SP2 = false>
; __device__ __forceinline__ void gemm_phase(PG8_LAS unsigned char* lds, const Gemm g, const Sched& S, const Epi& E) {
;     ...
;             PG8_WAIT_V(8); PG8_WAIT_L(0); PG8_BAR; PG8_MMA(1, 0, At, B0); PG8_MMA(1, 1, At, B1); PG8_BAR; PG8_SCHED;
;             PG8_LDB(B0, 1, 0); PG8_LDB(B1, 1, 1); PG8_SCHED; PG8_LDA(At, 1, 0); PG8_STAGE(PG8_SA(0, 1), a2 + hstep, voffA);
;             PG8_WAIT_V(8); PG8_WAIT_L(0); PG8_BAR; PG8_MMA(0, 0, At, B0); PG8_MMA(0, 1, At, B1); PG8_BAR; PG8_SCHED;
	s_setprio 1
	s_waitcnt lgkmcnt(0)
	v_mfma_f32_16x16x32_bf16 v[64:67], v[150:153], v[198:201], v[64:67]
	v_mfma_f32_16x16x32_bf16 v[64:67], v[154:157], v[202:205], v[64:67]
	v_mfma_f32_16x16x32_bf16 v[56:59], v[154:157], v[224:227], v[56:59]
	v_mfma_f32_16x16x32_bf16 v[56:59], v[150:153], v[220:223], v[56:59]
	v_mfma_f32_16x16x32_bf16 v[40:43], v[150:153], v[228:231], v[40:43]
	v_mfma_f32_16x16x32_bf16 v[40:43], v[154:157], v[232:235], v[40:43]
	v_mfma_f32_16x16x32_bf16 v[24:27], v[154:157], v[240:243], v[24:27]
	v_mfma_f32_16x16x32_bf16 v[24:27], v[150:153], v[236:239], v[24:27]
	v_mfma_f32_16x16x32_bf16 v[60:63], v[158:161], v[198:201], v[60:63]
	v_mfma_f32_16x16x32_bf16 v[60:63], v[162:165], v[202:205], v[60:63]
	v_mfma_f32_16x16x32_bf16 v[48:51], v[162:165], v[224:227], v[48:51]
	v_mfma_f32_16x16x32_bf16 v[48:51], v[158:161], v[220:223], v[48:51]
	v_mfma_f32_16x16x32_bf16 v[32:35], v[158:161], v[228:231], v[32:35]
	v_mfma_f32_16x16x32_bf16 v[32:35], v[162:165], v[232:235], v[32:35]
	v_mfma_f32_16x16x32_bf16 v[16:19], v[162:165], v[240:243], v[16:19]
	v_mfma_f32_16x16x32_bf16 v[16:19], v[158:161], v[236:239], v[16:19]
	s_setprio 0
	s_setprio 1
	v_mfma_f32_16x16x32_bf16 v[52:55], v[166:169], v[198:201], v[52:55]
	v_mfma_f32_16x16x32_bf16 v[52:55], v[170:173], v[202:205], v[52:55]
	v_mfma_f32_16x16x32_bf16 v[36:39], v[170:173], v[224:227], v[36:39]
	v_mfma_f32_16x16x32_bf16 v[36:39], v[166:169], v[220:223], v[36:39]
	v_mfma_f32_16x16x32_bf16 v[20:23], v[166:169], v[228:231], v[20:23]
	v_mfma_f32_16x16x32_bf16 v[20:23], v[170:173], v[232:235], v[20:23]
	v_mfma_f32_16x16x32_bf16 v[8:11], v[170:173], v[240:243], v[8:11]
	v_mfma_f32_16x16x32_bf16 v[8:11], v[166:169], v[236:239], v[8:11]
	v_mfma_f32_16x16x32_bf16 v[44:47], v[174:177], v[198:201], v[44:47]
	v_mfma_f32_16x16x32_bf16 v[44:47], v[178:181], v[202:205], v[44:47]
	v_mfma_f32_16x16x32_bf16 v[28:31], v[178:181], v[224:227], v[28:31]
	v_mfma_f32_16x16x32_bf16 v[28:31], v[174:177], v[220:223], v[28:31]
	v_mfma_f32_16x16x32_bf16 v[12:15], v[174:177], v[228:231], v[12:15]
	v_mfma_f32_16x16x32_bf16 v[12:15], v[178:181], v[232:235], v[12:15]
	v_mfma_f32_16x16x32_bf16 v[4:7], v[178:181], v[240:243], v[4:7]
	v_mfma_f32_16x16x32_bf16 v[4:7], v[174:177], v[236:239], v[4:7]
	s_setprio 0
	s_barrier
	s_add_i32 s44, 0, 0x18000
	v_add_u32_e32 v149, s44, v146
	s_add_i32 s45, 0, 0x1c000
	ds_read_b128 v[150:153], v149
	ds_read_b128 v[154:157], v149 offset:1024
	ds_read_b128 v[158:161], v149 offset:2048
	ds_read_b128 v[162:165], v149 offset:3072
	v_add_u32_e32 v149, s45, v146
	ds_read_b128 v[166:169], v149
	ds_read_b128 v[170:173], v149 offset:1024
	ds_read_b128 v[174:177], v149 offset:2048
	ds_read_b128 v[178:181], v149 offset:3072
	s_add_u32 s18, s18, 0x80000
	s_addc_u32 s19, s19, 0
	s_mov_b32 m0, s26
	v_lshl_add_u64 v[206:207], s[18:19], 0, v[136:137]
	ds_read_b128 v[198:201], v148 offset:32768
	ds_read_b128 v[202:205], v148 offset:33792
	ds_read_b128 v[220:223], v148 offset:34816
	ds_read_b128 v[224:227], v148 offset:35840
	ds_read_b128 v[228:231], v148 offset:36864
	ds_read_b128 v[232:235], v148 offset:37888
	ds_read_b128 v[236:239], v148 offset:38912
	ds_read_b128 v[240:243], v148 offset:39936
	global_load_lds_dwordx4 v[206:207], off
	v_lshl_add_u64 v[206:207], s[18:19], 0, v[134:135]
	s_mov_b32 m0, s27
	s_nop 0
	global_load_lds_dwordx4 v[206:207], off
	s_waitcnt vmcnt(8)
	s_waitcnt lgkmcnt(0)
	s_barrier
	s_setprio 1
	s_waitcnt lgkmcnt(0)
	v_mfma_f32_16x16x32_bf16 v[128:131], v[150:153], v[198:201], v[128:131]
	v_mfma_f32_16x16x32_bf16 v[128:131], v[154:157], v[202:205], v[128:131]
	v_mfma_f32_16x16x32_bf16 v[120:123], v[154:157], v[224:227], v[120:123]
	v_mfma_f32_16x16x32_bf16 v[120:123], v[150:153], v[220:223], v[120:123]
	v_mfma_f32_16x16x32_bf16 v[104:107], v[150:153], v[228:231], v[104:107]
	v_mfma_f32_16x16x32_bf16 v[104:107], v[154:157], v[232:235], v[104:107]
	v_mfma_f32_16x16x32_bf16 v[88:91], v[154:157], v[240:243], v[88:91]
	v_mfma_f32_16x16x32_bf16 v[88:91], v[150:153], v[236:239], v[88:91]
	v_mfma_f32_16x16x32_bf16 v[124:127], v[158:161], v[198:201], v[124:127]
	v_mfma_f32_16x16x32_bf16 v[124:127], v[162:165], v[202:205], v[124:127]
	v_mfma_f32_16x16x32_bf16 v[112:115], v[162:165], v[224:227], v[112:115]
	v_mfma_f32_16x16x32_bf16 v[112:115], v[158:161], v[220:223], v[112:115]
	v_mfma_f32_16x16x32_bf16 v[96:99], v[158:161], v[228:231], v[96:99]
	v_mfma_f32_16x16x32_bf16 v[96:99], v[162:165], v[232:235], v[96:99]
	v_mfma_f32_16x16x32_bf16 v[80:83], v[162:165], v[240:243], v[80:83]
	v_mfma_f32_16x16x32_bf16 v[80:83], v[158:161], v[236:239], v[80:83]
	s_setprio 0
	s_setprio 1
	v_mfma_f32_16x16x32_bf16 v[116:119], v[166:169], v[198:201], v[116:119]
	v_mfma_f32_16x16x32_bf16 v[116:119], v[170:173], v[202:205], v[116:119]
	v_mfma_f32_16x16x32_bf16 v[100:103], v[170:173], v[224:227], v[100:103]
	v_mfma_f32_16x16x32_bf16 v[100:103], v[166:169], v[220:223], v[100:103]
	v_mfma_f32_16x16x32_bf16 v[84:87], v[166:169], v[228:231], v[84:87]
	v_mfma_f32_16x16x32_bf16 v[84:87], v[170:173], v[232:235], v[84:87]
	v_mfma_f32_16x16x32_bf16 v[72:75], v[170:173], v[240:243], v[72:75]
	v_mfma_f32_16x16x32_bf16 v[72:75], v[166:169], v[236:239], v[72:75]
	v_mfma_f32_16x16x32_bf16 v[108:111], v[174:177], v[198:201], v[108:111]
	v_mfma_f32_16x16x32_bf16 v[108:111], v[178:181], v[202:205], v[108:111]
	v_mfma_f32_16x16x32_bf16 v[92:95], v[178:181], v[224:227], v[92:95]
	v_mfma_f32_16x16x32_bf16 v[92:95], v[174:177], v[220:223], v[92:95]
	v_mfma_f32_16x16x32_bf16 v[76:79], v[174:177], v[228:231], v[76:79]
	v_mfma_f32_16x16x32_bf16 v[76:79], v[178:181], v[232:235], v[76:79]
	v_mfma_f32_16x16x32_bf16 v[68:71], v[178:181], v[240:243], v[68:71]
	v_mfma_f32_16x16x32_bf16 v[68:71], v[174:177], v[236:239], v[68:71]
	s_setprio 0
	s_barrier
; #define PG8_STAGE(bufoff, gbase, voff) do { _Pragma("unroll") for (int _i = 0; _i < 2; ++_i) \
;         __builtin_amdgcn_global_load_lds((const unsigned*)((const char*)(gbase) + (voff)[_i]), (PG8_LAS unsigned*)(lds + (bufoff) + ldsw + _i * 8192), 16, 0, 0); } while (0)
; #define PG8_LDA(dst, b, h) do { _Pragma("unroll") for (int m = 0; m < 4; ++m) _Pragma("unroll") for (int k = 0; k < 2; ++k) dst[m][k] = *(const PG8_LAS bf16x8*)(lds + PG8_SA(b, h) + aoff + m * 2048 + k * 1024); } while (0)
; #define PG8_MMA(ai, bj, At, Bt) do { __builtin_amdgcn_s_setprio(1); _Pragma("unroll") for (int m = 0; m < 4; ++m) _Pragma("unroll") for (int n = 0; n < 2; ++n) _Pragma("unroll") for (int k = 0; k < 2; ++k) \
;         acc[ai][bj][m][n] = __builtin_amdgcn_mfma_f32_16x16x32_bf16(Bt[n][k], At[m][k], acc[ai][bj][m][n], 0, 0, 0); __builtin_amdgcn_s_setprio(0); } while (0)
; #define PG8_WAIT_V(n) asm volatile("s_waitcnt vmcnt(" #n ")" ::: "memory")
; #define PG8_WAIT_L(n) asm volatile("s_waitcnt lgkmcnt(" #n ")" ::: "memory")
; #define PG8_BAR __builtin_amdgcn_s_barrier()
; #define PG8_SCHED __builtin_amdgcn_sched_barrier(0)
; template <class Epi, class Sched, bool ALIGN_EPI = false, bool SP2 = false>
; __device__ __forceinline__ void gemm_phase(PG8_LAS unsigned char* lds, const Gemm g, const Sched& S, const Epi& E) {
;     ...
;         for (int t = 0; t < nt; t += 2) {
;             const bool last = (t == nt - 2);
;             const char* a1 = cA + (size_t)(t + 1) * kstep;
;             const char* a2 = last ? nA : cA + (size_t)(t + 2) * kstep; const char* b2 = last ? nB : cB + (size_t)(t + 2) * kstep;
;             const char* a3 = a2 + kstep; const char* b3 = b2 + kstep;
;     ...
;             PG8_LDA(At, 1, 1); PG8_STAGE(PG8_SB(1, 0), b3, voffB); PG8_STAGE(PG8_SB(1, 1), b3 + hstep, voffB); PG8_STAGE(PG8_SA(1, 0), a3, voffA);
;             PG8_WAIT_V(8); PG8_WAIT_L(0); PG8_BAR; PG8_MMA(1, 0, At, B0); PG8_MMA(1, 1, At, B1); PG8_BAR; PG8_SCHED;
	s_add_i32 s18, s44, s23
	v_lshl_add_u64 v[144:145], v[144:145], 0, s[34:35]
	s_mov_b32 m0, s18
	ds_read_b128 v[198:201], v148 offset:49152
	ds_read_b128 v[202:205], v148 offset:50176
	ds_read_b128 v[220:223], v148 offset:51200
	ds_read_b128 v[224:227], v148 offset:52224
	ds_read_b128 v[228:231], v148 offset:53248
	ds_read_b128 v[232:235], v148 offset:54272
	ds_read_b128 v[236:239], v148 offset:55296
	ds_read_b128 v[240:243], v148 offset:56320
	global_load_lds_dwordx4 v[144:145], off
	s_add_i32 m0, s18, 0x2000
	s_add_u32 s16, s16, 0x80080
	v_lshl_add_u64 v[144:145], v[184:185], 0, s[34:35]
	s_addc_u32 s17, s17, 0
	s_add_i32 s18, s45, s23
	global_load_lds_dwordx4 v[144:145], off
	v_lshl_add_u64 v[144:145], s[16:17], 0, v[2:3]
	s_mov_b32 m0, s18
	s_nop 0
	global_load_lds_dwordx4 v[144:145], off
	v_lshl_add_u64 v[144:145], s[16:17], 0, v[132:133]
	s_add_i32 m0, s18, 0x2000
	s_nop 0
	global_load_lds_dwordx4 v[144:145], off
	v_lshl_add_u64 v[144:145], v[186:187], 0, s[34:35]
	s_mov_b32 m0, s28
	s_nop 0
	global_load_lds_dwordx4 v[144:145], off
	v_lshl_add_u64 v[144:145], v[196:197], 0, s[34:35]
	s_mov_b32 m0, s29
	s_nop 0
	global_load_lds_dwordx4 v[144:145], off
	s_waitcnt vmcnt(8)
	s_waitcnt lgkmcnt(0)
	s_barrier
	s_setprio 1
	s_waitcnt lgkmcnt(0)
	v_mfma_f32_16x16x32_bf16 v[64:67], v[150:153], v[198:201], v[64:67]
	v_mfma_f32_16x16x32_bf16 v[64:67], v[154:157], v[202:205], v[64:67]
	v_mfma_f32_16x16x32_bf16 v[56:59], v[154:157], v[224:227], v[56:59]
	v_mfma_f32_16x16x32_bf16 v[56:59], v[150:153], v[220:223], v[56:59]
	v_mfma_f32_16x16x32_bf16 v[40:43], v[150:153], v[228:231], v[40:43]
	v_mfma_f32_16x16x32_bf16 v[40:43], v[154:157], v[232:235], v[40:43]
	v_mfma_f32_16x16x32_bf16 v[24:27], v[154:157], v[240:243], v[24:27]
	v_mfma_f32_16x16x32_bf16 v[24:27], v[150:153], v[236:239], v[24:27]
	v_mfma_f32_16x16x32_bf16 v[60:63], v[158:161], v[198:201], v[60:63]
	v_mfma_f32_16x16x32_bf16 v[60:63], v[162:165], v[202:205], v[60:63]
	v_mfma_f32_16x16x32_bf16 v[48:51], v[162:165], v[224:227], v[48:51]
	v_mfma_f32_16x16x32_bf16 v[48:51], v[158:161], v[220:223], v[48:51]
	v_mfma_f32_16x16x32_bf16 v[32:35], v[158:161], v[228:231], v[32:35]
	v_mfma_f32_16x16x32_bf16 v[32:35], v[162:165], v[232:235], v[32:35]
	v_mfma_f32_16x16x32_bf16 v[16:19], v[162:165], v[240:243], v[16:19]
	v_mfma_f32_16x16x32_bf16 v[16:19], v[158:161], v[236:239], v[16:19]
	s_setprio 0
	s_setprio 1
	v_mfma_f32_16x16x32_bf16 v[52:55], v[166:169], v[198:201], v[52:55]
	v_mfma_f32_16x16x32_bf16 v[52:55], v[170:173], v[202:205], v[52:55]
	v_mfma_f32_16x16x32_bf16 v[36:39], v[170:173], v[224:227], v[36:39]
	v_mfma_f32_16x16x32_bf16 v[36:39], v[166:169], v[220:223], v[36:39]
	v_mfma_f32_16x16x32_bf16 v[20:23], v[166:169], v[228:231], v[20:23]
	v_mfma_f32_16x16x32_bf16 v[20:23], v[170:173], v[232:235], v[20:23]
	v_mfma_f32_16x16x32_bf16 v[8:11], v[170:173], v[240:243], v[8:11]
	v_mfma_f32_16x16x32_bf16 v[8:11], v[166:169], v[236:239], v[8:11]
	v_mfma_f32_16x16x32_bf16 v[44:47], v[174:177], v[198:201], v[44:47]
	v_mfma_f32_16x16x32_bf16 v[44:47], v[178:181], v[202:205], v[44:47]
	v_mfma_f32_16x16x32_bf16 v[28:31], v[178:181], v[224:227], v[28:31]
	v_mfma_f32_16x16x32_bf16 v[28:31], v[174:177], v[220:223], v[28:31]
	v_mfma_f32_16x16x32_bf16 v[12:15], v[174:177], v[228:231], v[12:15]
	v_mfma_f32_16x16x32_bf16 v[12:15], v[178:181], v[232:235], v[12:15]
	v_mfma_f32_16x16x32_bf16 v[4:7], v[178:181], v[240:243], v[4:7]
	v_mfma_f32_16x16x32_bf16 v[4:7], v[174:177], v[236:239], v[4:7]
	s_setprio 0
	s_barrier
	s_add_i32 s43, s43, 2
	s_add_u32 s14, s14, 0x100
	s_addc_u32 s15, s15, 0
	s_add_u32 s41, s41, 0x100
	s_addc_u32 s42, s42, 0
	s_cmp_gt_u32 s43, 29
	s_cbranch_scc0 .LBB11_913
	s_and_b64 vcc, exec, s[4:5]
	s_cbranch_vccz .LBB11_916
	s_barrier

; #define PG8_STAGE(bufoff, gbase, voff) do { _Pragma("unroll") for (int _i = 0; _i < 2; ++_i) \
;         __builtin_amdgcn_global_load_lds((const unsigned*)((const char*)(gbase) + (voff)[_i]), (PG8_LAS unsigned*)(lds + (bufoff) + ldsw + _i * 8192), 16, 0, 0); } while (0)
; #define PG8_LDA(dst, b, h) do { _Pragma("unroll") for (int m = 0; m < 4; ++m) _Pragma("unroll") for (int k = 0; k < 2; ++k) dst[m][k] = *(const PG8_LAS bf16x8*)(lds + PG8_SA(b, h) + aoff + m * 2048 + k * 1024); } while (0)
; #define PG8_LDB(dst, b, h) do { _Pragma("unroll") for (int n = 0; n < 2; ++n) _Pragma("unroll") for (int k = 0; k < 2; ++k) dst[n][k] = *(const PG8_LAS bf16x8*)(lds + PG8_SB(b, h) + boff + n * 2048 + k * 1024); } while (0)
; #define PG8_MMA(ai, bj, At, Bt) do { __builtin_amdgcn_s_setprio(1); _Pragma("unroll") for (int m = 0; m < 4; ++m) _Pragma("unroll") for (int n = 0; n < 2; ++n) _Pragma("unroll") for (int k = 0; k < 2; ++k) \
;         acc[ai][bj][m][n] = __builtin_amdgcn_mfma_f32_16x16x32_bf16(Bt[n][k], At[m][k], acc[ai][bj][m][n], 0, 0, 0); __builtin_amdgcn_s_setprio(0); } while (0)
; #define PG8_WAIT_V(n) asm volatile("s_waitcnt vmcnt(" #n ")" ::: "memory")
; #define PG8_WAIT_L(n) asm volatile("s_waitcnt lgkmcnt(" #n ")" ::: "memory")
; template <class Epi, class Sched, bool ALIGN_EPI = false, bool SP2 = false>
; __device__ __forceinline__ void gemm_phase(PG8_LAS unsigned char* lds, const Gemm g, const Sched& S, const Epi& E) {
;     ...
;             const bool last = (t == nt - 2);
;             const char* a1 = cA + (size_t)(t + 1) * kstep;
;             const char* a2 = last ? nA : cA + (size_t)(t + 2) * kstep; const char* b2 = last ? nB : cB + (size_t)(t + 2) * kstep;
;             const char* a3 = a2 + kstep; const char* b3 = b2 + kstep;
;             if (last && has_next) S.a_ready(nxt);
;             if constexpr (SP2) {
;             PG8_LDB(B0, 0, 0); PG8_LDB(B1, 0, 1); PG8_SCHED; PG8_LDA(At, 0, 0); PG8_STAGE(PG8_SA(1, 1), a1 + hstep, voffA);
;             PG8_WAIT_V(8); PG8_WAIT_L(0); PG8_BAR; PG8_MMA(0, 0, At, B0); PG8_MMA(0, 1, At, B1); PG8_BAR; PG8_SCHED;
;             PG8_LDA(At, 0, 1); PG8_STAGE(PG8_SB(0, 0), b2, voffB); PG8_STAGE(PG8_SB(0, 1), b2 + hstep, voffB); PG8_STAGE(PG8_SA(0, 0), a2, voffA);
;             PG8_WAIT_V(8); PG8_WAIT_L(0); PG8_BAR; PG8_MMA(1, 0, At, B0); PG8_MMA(1, 1, At, B1); PG8_BAR; PG8_SCHED;
.LBB11_1071:
	s_add_u32 s16, s14, 0xfff80080
	s_addc_u32 s17, s15, -1
	s_add_i32 s46, 0, 0x10000
	s_cmp_eq_u32 s45, 28
	s_cselect_b32 s19, s9, s17
	s_cselect_b32 s18, s41, s16
	v_add_u32_e32 v2, s46, v168
	s_cselect_b32 s17, s7, s44
	s_cselect_b32 s16, s42, s43
	s_add_i32 s48, 0, 0x14000
	ds_read_b128 v[132:135], v2
	ds_read_b128 v[136:139], v2 offset:1024
	ds_read_b128 v[140:143], v2 offset:2048
	ds_read_b128 v[144:147], v2 offset:3072
	v_add_u32_e32 v2, s48, v168
	ds_read_b128 v[170:173], v2
	ds_read_b128 v[174:177], v2 offset:1024
	ds_read_b128 v[178:181], v2 offset:2048
	ds_read_b128 v[198:201], v2 offset:3072
	v_lshl_add_u64 v[166:167], s[14:15], 0, v[162:163]
	s_add_i32 m0, s25, 0xc000
	ds_read_b128 v[202:205], v169
	ds_read_b128 v[220:223], v169 offset:1024
	ds_read_b128 v[224:227], v169 offset:2048
	ds_read_b128 v[228:231], v169 offset:3072
	ds_read_b128 v[232:235], v169 offset:4096
	ds_read_b128 v[236:239], v169 offset:5120
	ds_read_b128 v[240:243], v169 offset:6144
	ds_read_b128 v[244:247], v169 offset:7168
	global_load_lds_dwordx4 v[166:167], off
	v_lshl_add_u64 v[166:167], s[14:15], 0, v[164:165]
	s_add_i32 m0, s25, 0xe000
	s_nop 0
	global_load_lds_dwordx4 v[166:167], off
	s_waitcnt vmcnt(8)
	s_waitcnt lgkmcnt(0)
	s_barrier
	s_setprio 1
	s_waitcnt lgkmcnt(0)
	v_mfma_f32_16x16x32_bf16 v[128:131], v[132:135], v[202:205], v[128:131]
	v_mfma_f32_16x16x32_bf16 v[128:131], v[136:139], v[220:223], v[128:131]
	v_mfma_f32_16x16x32_bf16 v[120:123], v[136:139], v[228:231], v[120:123]
	v_mfma_f32_16x16x32_bf16 v[120:123], v[132:135], v[224:227], v[120:123]
	v_mfma_f32_16x16x32_bf16 v[104:107], v[132:135], v[232:235], v[104:107]
	v_mfma_f32_16x16x32_bf16 v[104:107], v[136:139], v[236:239], v[104:107]
	v_mfma_f32_16x16x32_bf16 v[88:91], v[136:139], v[244:247], v[88:91]
	v_mfma_f32_16x16x32_bf16 v[88:91], v[132:135], v[240:243], v[88:91]
	v_mfma_f32_16x16x32_bf16 v[124:127], v[140:143], v[202:205], v[124:127]
	v_mfma_f32_16x16x32_bf16 v[124:127], v[144:147], v[220:223], v[124:127]
	v_mfma_f32_16x16x32_bf16 v[112:115], v[144:147], v[228:231], v[112:115]
	v_mfma_f32_16x16x32_bf16 v[112:115], v[140:143], v[224:227], v[112:115]
	v_mfma_f32_16x16x32_bf16 v[96:99], v[140:143], v[232:235], v[96:99]
	v_mfma_f32_16x16x32_bf16 v[96:99], v[144:147], v[236:239], v[96:99]
	v_mfma_f32_16x16x32_bf16 v[80:83], v[144:147], v[244:247], v[80:83]
	v_mfma_f32_16x16x32_bf16 v[80:83], v[140:143], v[240:243], v[80:83]
	s_setprio 0
	s_setprio 1
	v_mfma_f32_16x16x32_bf16 v[116:119], v[170:173], v[202:205], v[116:119]
	v_mfma_f32_16x16x32_bf16 v[116:119], v[174:177], v[220:223], v[116:119]
	v_mfma_f32_16x16x32_bf16 v[100:103], v[174:177], v[228:231], v[100:103]
	v_mfma_f32_16x16x32_bf16 v[100:103], v[170:173], v[224:227], v[100:103]
	v_mfma_f32_16x16x32_bf16 v[84:87], v[170:173], v[232:235], v[84:87]
	v_mfma_f32_16x16x32_bf16 v[84:87], v[174:177], v[236:239], v[84:87]
	v_mfma_f32_16x16x32_bf16 v[72:75], v[174:177], v[244:247], v[72:75]
	v_mfma_f32_16x16x32_bf16 v[72:75], v[170:173], v[240:243], v[72:75]
	v_mfma_f32_16x16x32_bf16 v[108:111], v[178:181], v[202:205], v[108:111]
	v_mfma_f32_16x16x32_bf16 v[108:111], v[198:201], v[220:223], v[108:111]
	v_mfma_f32_16x16x32_bf16 v[92:95], v[198:201], v[228:231], v[92:95]
	v_mfma_f32_16x16x32_bf16 v[92:95], v[178:181], v[224:227], v[92:95]
	v_mfma_f32_16x16x32_bf16 v[76:79], v[178:181], v[232:235], v[76:79]
	v_mfma_f32_16x16x32_bf16 v[76:79], v[198:201], v[236:239], v[76:79]
	v_mfma_f32_16x16x32_bf16 v[68:71], v[198:201], v[244:247], v[68:71]
	v_mfma_f32_16x16x32_bf16 v[68:71], v[178:181], v[240:243], v[68:71]
	s_setprio 0
	s_barrier
	s_add_i32 s46, s46, s24
	v_lshl_add_u64 v[166:167], s[16:17], 0, v[154:155]
	s_mov_b32 m0, s46
	ds_read_b128 v[202:205], v169 offset:16384
	ds_read_b128 v[220:223], v169 offset:17408
	ds_read_b128 v[224:227], v169 offset:18432
	ds_read_b128 v[228:231], v169 offset:19456
	ds_read_b128 v[232:235], v169 offset:20480
	ds_read_b128 v[236:239], v169 offset:21504
	ds_read_b128 v[240:243], v169 offset:22528
	ds_read_b128 v[244:247], v169 offset:23552
	global_load_lds_dwordx4 v[166:167], off
	s_add_i32 m0, s46, 0x2000
	s_add_u32 s46, s16, 0x80000
	v_lshl_add_u64 v[196:197], s[16:17], 0, v[150:151]
	s_addc_u32 s47, s17, 0
	s_add_i32 s48, s48, s24
	global_load_lds_dwordx4 v[196:197], off
	v_lshl_add_u64 v[206:207], s[46:47], 0, v[154:155]
	s_mov_b32 m0, s48
	v_lshl_add_u64 v[184:185], s[18:19], 0, v[152:153]
	global_load_lds_dwordx4 v[206:207], off
	v_lshl_add_u64 v[206:207], s[46:47], 0, v[150:151]
	s_add_i32 m0, s48, 0x2000
	s_nop 0
	global_load_lds_dwordx4 v[206:207], off
	v_lshl_add_u64 v[206:207], s[18:19], 0, v[156:157]
	s_mov_b32 m0, s25
	s_nop 0
	global_load_lds_dwordx4 v[206:207], off
	s_mov_b32 m0, s26
	s_nop 0
	global_load_lds_dwordx4 v[184:185], off
	s_waitcnt vmcnt(8)
	s_waitcnt lgkmcnt(0)
	s_barrier
; #define PG8_STAGE(bufoff, gbase, voff) do { _Pragma("unroll") for (int _i = 0; _i < 2; ++_i) \
;         __builtin_amdgcn_global_load_lds((const unsigned*)((const char*)(gbase) + (voff)[_i]), (PG8_LAS unsigned*)(lds + (bufoff) + ldsw + _i * 8192), 16, 0, 0); } while (0)
; #define PG8_LDA(dst, b, h) do { _Pragma("unroll") for (int m = 0; m < 4; ++m) _Pragma("unroll") for (int k = 0; k < 2; ++k) dst[m][k] = *(const PG8_LAS bf16x8*)(lds + PG8_SA(b, h) + aoff + m * 2048 + k * 1024); } while (0)
; #define PG8_LDB(dst, b, h) do { _Pragma("unroll") for (int n = 0; n < 2; ++n) _Pragma("unroll") for (int k = 0; k < 2; ++k) dst[n][k] = *(const PG8_LAS bf16x8*)(lds + PG8_SB(b, h) + boff + n * 2048 + k * 1024); } while (0)
; #define PG8_MMA(ai, bj, At, Bt) do { __builtin_amdgcn_s_setprio(1); _Pragma("unroll") for (int m = 0; m < 4; ++m) _Pragma("unroll") for (int n = 0; n < 2; ++n) _Pragma("unroll") for (int k = 0; k < 2; ++k) \
;         acc[ai][bj][m][n] = __builtin_amdgcn_mfma_f32_16x16x32_bf16(Bt[n][k], At[m][k], acc[ai][bj][m][n], 0, 0, 0); __builtin_amdgcn_s_setprio(0); } while (0)
; #define PG8_WAIT_V(n) asm volatile("s_waitcnt vmcnt(" #n ")" ::: "memory")
; #define PG8_WAIT_L(n) asm volatile("s_waitcnt lgkmcnt(" #n ")" ::: "memory")
; #define PG8_BAR __builtin_amdgcn_s_barrier()
; #define PG8_SCHED __builtin_amdgcn_sched_barrier(0)
; template <class Epi, class Sched, bool ALIGN_EPI = false, bool SP2 = false>
; __device__ __forceinline__ void gemm_phase(PG8_LAS unsigned char* lds, const Gemm g, const Sched& S, const Epi& E) {
;     ...
;             PG8_WAIT_V(8); PG8_WAIT_L(0); PG8_BAR; PG8_MMA(1, 0, At, B0); PG8_MMA(1, 1, At, B1); PG8_BAR; PG8_SCHED;
;             PG8_LDB(B0, 1, 0); PG8_LDB(B1, 1, 1); PG8_SCHED; PG8_LDA(At, 1, 0); PG8_STAGE(PG8_SA(0, 1), a2 + hstep, voffA);
;             PG8_WAIT_V(8); PG8_WAIT_L(0); PG8_BAR; PG8_MMA(0, 0, At, B0); PG8_MMA(0, 1, At, B1); PG8_BAR; PG8_SCHED;
	s_setprio 1
	s_waitcnt lgkmcnt(0)
	v_mfma_f32_16x16x32_bf16 v[64:67], v[132:135], v[202:205], v[64:67]
	v_mfma_f32_16x16x32_bf16 v[64:67], v[136:139], v[220:223], v[64:67]
	v_mfma_f32_16x16x32_bf16 v[56:59], v[136:139], v[228:231], v[56:59]
	v_mfma_f32_16x16x32_bf16 v[56:59], v[132:135], v[224:227], v[56:59]
	v_mfma_f32_16x16x32_bf16 v[40:43], v[132:135], v[232:235], v[40:43]
	v_mfma_f32_16x16x32_bf16 v[40:43], v[136:139], v[236:239], v[40:43]
	v_mfma_f32_16x16x32_bf16 v[24:27], v[136:139], v[244:247], v[24:27]
	v_mfma_f32_16x16x32_bf16 v[24:27], v[132:135], v[240:243], v[24:27]
	v_mfma_f32_16x16x32_bf16 v[60:63], v[140:143], v[202:205], v[60:63]
	v_mfma_f32_16x16x32_bf16 v[60:63], v[144:147], v[220:223], v[60:63]
	v_mfma_f32_16x16x32_bf16 v[48:51], v[144:147], v[228:231], v[48:51]
	v_mfma_f32_16x16x32_bf16 v[48:51], v[140:143], v[224:227], v[48:51]
	v_mfma_f32_16x16x32_bf16 v[32:35], v[140:143], v[232:235], v[32:35]
	v_mfma_f32_16x16x32_bf16 v[32:35], v[144:147], v[236:239], v[32:35]
	v_mfma_f32_16x16x32_bf16 v[16:19], v[144:147], v[244:247], v[16:19]
	v_mfma_f32_16x16x32_bf16 v[16:19], v[140:143], v[240:243], v[16:19]
	s_setprio 0
	s_setprio 1
	v_mfma_f32_16x16x32_bf16 v[52:55], v[170:173], v[202:205], v[52:55]
	v_mfma_f32_16x16x32_bf16 v[52:55], v[174:177], v[220:223], v[52:55]
	v_mfma_f32_16x16x32_bf16 v[36:39], v[174:177], v[228:231], v[36:39]
	v_mfma_f32_16x16x32_bf16 v[36:39], v[170:173], v[224:227], v[36:39]
	v_mfma_f32_16x16x32_bf16 v[20:23], v[170:173], v[232:235], v[20:23]
	v_mfma_f32_16x16x32_bf16 v[20:23], v[174:177], v[236:239], v[20:23]
	v_mfma_f32_16x16x32_bf16 v[8:11], v[174:177], v[244:247], v[8:11]
	v_mfma_f32_16x16x32_bf16 v[8:11], v[170:173], v[240:243], v[8:11]
	v_mfma_f32_16x16x32_bf16 v[44:47], v[178:181], v[202:205], v[44:47]
	v_mfma_f32_16x16x32_bf16 v[44:47], v[198:201], v[220:223], v[44:47]
	v_mfma_f32_16x16x32_bf16 v[28:31], v[198:201], v[228:231], v[28:31]
	v_mfma_f32_16x16x32_bf16 v[28:31], v[178:181], v[224:227], v[28:31]
	v_mfma_f32_16x16x32_bf16 v[12:15], v[178:181], v[232:235], v[12:15]
	v_mfma_f32_16x16x32_bf16 v[12:15], v[198:201], v[236:239], v[12:15]
	v_mfma_f32_16x16x32_bf16 v[4:7], v[198:201], v[244:247], v[4:7]
	v_mfma_f32_16x16x32_bf16 v[4:7], v[178:181], v[240:243], v[4:7]
	s_setprio 0
	s_barrier
	s_add_i32 s46, 0, 0x18000
	v_add_u32_e32 v2, s46, v168
	s_add_i32 s47, 0, 0x1c000
	ds_read_b128 v[132:135], v2
	ds_read_b128 v[136:139], v2 offset:1024
	ds_read_b128 v[140:143], v2 offset:2048
	ds_read_b128 v[144:147], v2 offset:3072
	v_add_u32_e32 v2, s47, v168
	ds_read_b128 v[170:173], v2
	ds_read_b128 v[174:177], v2 offset:1024
	ds_read_b128 v[178:181], v2 offset:2048
	ds_read_b128 v[198:201], v2 offset:3072
	s_add_u32 s18, s18, 0x80000
	s_addc_u32 s19, s19, 0
	s_mov_b32 m0, s27
	v_lshl_add_u64 v[186:187], s[18:19], 0, v[156:157]
	ds_read_b128 v[202:205], v169 offset:32768
	ds_read_b128 v[220:223], v169 offset:33792
	ds_read_b128 v[224:227], v169 offset:34816
	ds_read_b128 v[228:231], v169 offset:35840
	ds_read_b128 v[232:235], v169 offset:36864
	ds_read_b128 v[236:239], v169 offset:37888
	ds_read_b128 v[240:243], v169 offset:38912
	ds_read_b128 v[244:247], v169 offset:39936
	global_load_lds_dwordx4 v[186:187], off
	v_lshl_add_u64 v[186:187], s[18:19], 0, v[152:153]
	s_mov_b32 m0, s28
	s_nop 0
	global_load_lds_dwordx4 v[186:187], off
	s_waitcnt vmcnt(8)
	s_waitcnt lgkmcnt(0)
	s_barrier
	s_setprio 1
	s_waitcnt lgkmcnt(0)
	v_mfma_f32_16x16x32_bf16 v[128:131], v[132:135], v[202:205], v[128:131]
	v_mfma_f32_16x16x32_bf16 v[128:131], v[136:139], v[220:223], v[128:131]
	v_mfma_f32_16x16x32_bf16 v[120:123], v[136:139], v[228:231], v[120:123]
	v_mfma_f32_16x16x32_bf16 v[120:123], v[132:135], v[224:227], v[120:123]
	v_mfma_f32_16x16x32_bf16 v[104:107], v[132:135], v[232:235], v[104:107]
	v_mfma_f32_16x16x32_bf16 v[104:107], v[136:139], v[236:239], v[104:107]
	v_mfma_f32_16x16x32_bf16 v[88:91], v[136:139], v[244:247], v[88:91]
	v_mfma_f32_16x16x32_bf16 v[88:91], v[132:135], v[240:243], v[88:91]
	v_mfma_f32_16x16x32_bf16 v[124:127], v[140:143], v[202:205], v[124:127]
	v_mfma_f32_16x16x32_bf16 v[124:127], v[144:147], v[220:223], v[124:127]
	v_mfma_f32_16x16x32_bf16 v[112:115], v[144:147], v[228:231], v[112:115]
	v_mfma_f32_16x16x32_bf16 v[112:115], v[140:143], v[224:227], v[112:115]
	v_mfma_f32_16x16x32_bf16 v[96:99], v[140:143], v[232:235], v[96:99]
	v_mfma_f32_16x16x32_bf16 v[96:99], v[144:147], v[236:239], v[96:99]
	v_mfma_f32_16x16x32_bf16 v[80:83], v[144:147], v[244:247], v[80:83]
	v_mfma_f32_16x16x32_bf16 v[80:83], v[140:143], v[240:243], v[80:83]
	s_setprio 0
	s_setprio 1
	v_mfma_f32_16x16x32_bf16 v[116:119], v[170:173], v[202:205], v[116:119]
	v_mfma_f32_16x16x32_bf16 v[116:119], v[174:177], v[220:223], v[116:119]
	v_mfma_f32_16x16x32_bf16 v[100:103], v[174:177], v[228:231], v[100:103]
	v_mfma_f32_16x16x32_bf16 v[100:103], v[170:173], v[224:227], v[100:103]
	v_mfma_f32_16x16x32_bf16 v[84:87], v[170:173], v[232:235], v[84:87]
	v_mfma_f32_16x16x32_bf16 v[84:87], v[174:177], v[236:239], v[84:87]
	v_mfma_f32_16x16x32_bf16 v[72:75], v[174:177], v[244:247], v[72:75]
	v_mfma_f32_16x16x32_bf16 v[72:75], v[170:173], v[240:243], v[72:75]
	v_mfma_f32_16x16x32_bf16 v[108:111], v[178:181], v[202:205], v[108:111]
	v_mfma_f32_16x16x32_bf16 v[108:111], v[198:201], v[220:223], v[108:111]
	v_mfma_f32_16x16x32_bf16 v[92:95], v[198:201], v[228:231], v[92:95]
	v_mfma_f32_16x16x32_bf16 v[92:95], v[178:181], v[224:227], v[92:95]
	v_mfma_f32_16x16x32_bf16 v[76:79], v[178:181], v[232:235], v[76:79]
	v_mfma_f32_16x16x32_bf16 v[76:79], v[198:201], v[236:239], v[76:79]
	v_mfma_f32_16x16x32_bf16 v[68:71], v[198:201], v[244:247], v[68:71]
	v_mfma_f32_16x16x32_bf16 v[68:71], v[178:181], v[240:243], v[68:71]
	s_setprio 0
	s_barrier
; #define PG8_STAGE(bufoff, gbase, voff) do { _Pragma("unroll") for (int _i = 0; _i < 2; ++_i) \
;         __builtin_amdgcn_global_load_lds((const unsigned*)((const char*)(gbase) + (voff)[_i]), (PG8_LAS unsigned*)(lds + (bufoff) + ldsw + _i * 8192), 16, 0, 0); } while (0)
; #define PG8_LDA(dst, b, h) do { _Pragma("unroll") for (int m = 0; m < 4; ++m) _Pragma("unroll") for (int k = 0; k < 2; ++k) dst[m][k] = *(const PG8_LAS bf16x8*)(lds + PG8_SA(b, h) + aoff + m * 2048 + k * 1024); } while (0)
; #define PG8_MMA(ai, bj, At, Bt) do { __builtin_amdgcn_s_setprio(1); _Pragma("unroll") for (int m = 0; m < 4; ++m) _Pragma("unroll") for (int n = 0; n < 2; ++n) _Pragma("unroll") for (int k = 0; k < 2; ++k) \
;         acc[ai][bj][m][n] = __builtin_amdgcn_mfma_f32_16x16x32_bf16(Bt[n][k], At[m][k], acc[ai][bj][m][n], 0, 0, 0); __builtin_amdgcn_s_setprio(0); } while (0)
; #define PG8_WAIT_V(n) asm volatile("s_waitcnt vmcnt(" #n ")" ::: "memory")
; #define PG8_WAIT_L(n) asm volatile("s_waitcnt lgkmcnt(" #n ")" ::: "memory")
; #define PG8_BAR __builtin_amdgcn_s_barrier()
; #define PG8_SCHED __builtin_amdgcn_sched_barrier(0)
; template <class Epi, class Sched, bool ALIGN_EPI = false, bool SP2 = false>
; __device__ __forceinline__ void gemm_phase(PG8_LAS unsigned char* lds, const Gemm g, const Sched& S, const Epi& E) {
;     ...
;         for (int t = 0; t < nt; t += 2) {
;             const bool last = (t == nt - 2);
;             const char* a1 = cA + (size_t)(t + 1) * kstep;
;             const char* a2 = last ? nA : cA + (size_t)(t + 2) * kstep; const char* b2 = last ? nB : cB + (size_t)(t + 2) * kstep;
;             const char* a3 = a2 + kstep; const char* b3 = b2 + kstep;
;     ...
;             PG8_LDA(At, 1, 1); PG8_STAGE(PG8_SB(1, 0), b3, voffB); PG8_STAGE(PG8_SB(1, 1), b3 + hstep, voffB); PG8_STAGE(PG8_SA(1, 0), a3, voffA);
;             PG8_WAIT_V(8); PG8_WAIT_L(0); PG8_BAR; PG8_MMA(1, 0, At, B0); PG8_MMA(1, 1, At, B1); PG8_BAR; PG8_SCHED;
	s_add_i32 s18, s46, s24
	v_lshl_add_u64 v[166:167], v[166:167], 0, s[34:35]
	s_mov_b32 m0, s18
	ds_read_b128 v[202:205], v169 offset:49152
	ds_read_b128 v[220:223], v169 offset:50176
	ds_read_b128 v[224:227], v169 offset:51200
	ds_read_b128 v[228:231], v169 offset:52224
	ds_read_b128 v[232:235], v169 offset:53248
	ds_read_b128 v[236:239], v169 offset:54272
	ds_read_b128 v[240:243], v169 offset:55296
	ds_read_b128 v[244:247], v169 offset:56320
	global_load_lds_dwordx4 v[166:167], off
	s_add_i32 m0, s18, 0x2000
	s_add_u32 s16, s16, 0x80080
	v_lshl_add_u64 v[166:167], v[196:197], 0, s[34:35]
	s_addc_u32 s17, s17, 0
	s_add_i32 s18, s47, s24
	global_load_lds_dwordx4 v[166:167], off
	v_lshl_add_u64 v[166:167], s[16:17], 0, v[154:155]
	s_mov_b32 m0, s18
	s_nop 0
	global_load_lds_dwordx4 v[166:167], off
	v_lshl_add_u64 v[166:167], s[16:17], 0, v[150:151]
	s_add_i32 m0, s18, 0x2000
	s_nop 0
	global_load_lds_dwordx4 v[166:167], off
	v_lshl_add_u64 v[166:167], v[206:207], 0, s[34:35]
	s_mov_b32 m0, s33
	s_nop 0
	global_load_lds_dwordx4 v[166:167], off
	v_lshl_add_u64 v[166:167], v[184:185], 0, s[34:35]
	s_mov_b32 m0, s38
	s_nop 0
	global_load_lds_dwordx4 v[166:167], off
	s_waitcnt vmcnt(8)
	s_waitcnt lgkmcnt(0)
	s_barrier
	s_setprio 1
	s_waitcnt lgkmcnt(0)
	v_mfma_f32_16x16x32_bf16 v[64:67], v[132:135], v[202:205], v[64:67]
	v_mfma_f32_16x16x32_bf16 v[64:67], v[136:139], v[220:223], v[64:67]
	v_mfma_f32_16x16x32_bf16 v[56:59], v[136:139], v[228:231], v[56:59]
	v_mfma_f32_16x16x32_bf16 v[56:59], v[132:135], v[224:227], v[56:59]
	v_mfma_f32_16x16x32_bf16 v[40:43], v[132:135], v[232:235], v[40:43]
	v_mfma_f32_16x16x32_bf16 v[40:43], v[136:139], v[236:239], v[40:43]
	v_mfma_f32_16x16x32_bf16 v[24:27], v[136:139], v[244:247], v[24:27]
	v_mfma_f32_16x16x32_bf16 v[24:27], v[132:135], v[240:243], v[24:27]
	v_mfma_f32_16x16x32_bf16 v[60:63], v[140:143], v[202:205], v[60:63]
	v_mfma_f32_16x16x32_bf16 v[60:63], v[144:147], v[220:223], v[60:63]
	v_mfma_f32_16x16x32_bf16 v[48:51], v[144:147], v[228:231], v[48:51]
	v_mfma_f32_16x16x32_bf16 v[48:51], v[140:143], v[224:227], v[48:51]
	v_mfma_f32_16x16x32_bf16 v[32:35], v[140:143], v[232:235], v[32:35]
	v_mfma_f32_16x16x32_bf16 v[32:35], v[144:147], v[236:239], v[32:35]
	v_mfma_f32_16x16x32_bf16 v[16:19], v[144:147], v[244:247], v[16:19]
	v_mfma_f32_16x16x32_bf16 v[16:19], v[140:143], v[240:243], v[16:19]
	s_setprio 0
	s_setprio 1
	v_mfma_f32_16x16x32_bf16 v[52:55], v[170:173], v[202:205], v[52:55]
	v_mfma_f32_16x16x32_bf16 v[52:55], v[174:177], v[220:223], v[52:55]
	v_mfma_f32_16x16x32_bf16 v[36:39], v[174:177], v[228:231], v[36:39]
	v_mfma_f32_16x16x32_bf16 v[36:39], v[170:173], v[224:227], v[36:39]
	v_mfma_f32_16x16x32_bf16 v[20:23], v[170:173], v[232:235], v[20:23]
	v_mfma_f32_16x16x32_bf16 v[20:23], v[174:177], v[236:239], v[20:23]
	v_mfma_f32_16x16x32_bf16 v[8:11], v[174:177], v[244:247], v[8:11]
	v_mfma_f32_16x16x32_bf16 v[8:11], v[170:173], v[240:243], v[8:11]
	v_mfma_f32_16x16x32_bf16 v[44:47], v[178:181], v[202:205], v[44:47]
	v_mfma_f32_16x16x32_bf16 v[44:47], v[198:201], v[220:223], v[44:47]
	v_mfma_f32_16x16x32_bf16 v[28:31], v[198:201], v[228:231], v[28:31]
	v_mfma_f32_16x16x32_bf16 v[28:31], v[178:181], v[224:227], v[28:31]
	v_mfma_f32_16x16x32_bf16 v[12:15], v[178:181], v[232:235], v[12:15]
	v_mfma_f32_16x16x32_bf16 v[12:15], v[198:201], v[236:239], v[12:15]
	v_mfma_f32_16x16x32_bf16 v[4:7], v[198:201], v[244:247], v[4:7]
	v_mfma_f32_16x16x32_bf16 v[4:7], v[178:181], v[240:243], v[4:7]
	s_setprio 0
	s_barrier
	s_add_i32 s45, s45, 2
	s_add_u32 s14, s14, 0x100
	s_addc_u32 s15, s15, 0
	s_add_u32 s43, s43, 0x100
	s_addc_u32 s44, s44, 0
	s_cmp_gt_u32 s45, 29
	s_cbranch_scc0 .LBB11_1071
	s_and_b64 vcc, exec, s[4:5]
	s_cbranch_vccz .LBB11_1074
	s_barrier

; #define PG8_STAGE(bufoff, gbase, voff) do { _Pragma("unroll") for (int _i = 0; _i < 2; ++_i) \
;         __builtin_amdgcn_global_load_lds((const unsigned*)((const char*)(gbase) + (voff)[_i]), (PG8_LAS unsigned*)(lds + (bufoff) + ldsw + _i * 8192), 16, 0, 0); } while (0)
; #define PG8_LDA(dst, b, h) do { _Pragma("unroll") for (int m = 0; m < 4; ++m) _Pragma("unroll") for (int k = 0; k < 2; ++k) dst[m][k] = *(const PG8_LAS bf16x8*)(lds + PG8_SA(b, h) + aoff + m * 2048 + k * 1024); } while (0)
; #define PG8_LDB(dst, b, h) do { _Pragma("unroll") for (int n = 0; n < 2; ++n) _Pragma("unroll") for (int k = 0; k < 2; ++k) dst[n][k] = *(const PG8_LAS bf16x8*)(lds + PG8_SB(b, h) + boff + n * 2048 + k * 1024); } while (0)
; #define PG8_MMA(ai, bj, At, Bt) do { __builtin_amdgcn_s_setprio(1); _Pragma("unroll") for (int m = 0; m < 4; ++m) _Pragma("unroll") for (int n = 0; n < 2; ++n) _Pragma("unroll") for (int k = 0; k < 2; ++k) \
;         acc[ai][bj][m][n] = __builtin_amdgcn_mfma_f32_16x16x32_bf16(Bt[n][k], At[m][k], acc[ai][bj][m][n], 0, 0, 0); __builtin_amdgcn_s_setprio(0); } while (0)
; #define PG8_WAIT_V(n) asm volatile("s_waitcnt vmcnt(" #n ")" ::: "memory")
; #define PG8_WAIT_L(n) asm volatile("s_waitcnt lgkmcnt(" #n ")" ::: "memory")
; template <class Epi, class Sched, bool ALIGN_EPI = false, bool SP2 = false>
; __device__ __forceinline__ void gemm_phase(PG8_LAS unsigned char* lds, const Gemm g, const Sched& S, const Epi& E) {
;     ...
;             const bool last = (t == nt - 2);
;             const char* a1 = cA + (size_t)(t + 1) * kstep;
;             const char* a2 = last ? nA : cA + (size_t)(t + 2) * kstep; const char* b2 = last ? nB : cB + (size_t)(t + 2) * kstep;
;             const char* a3 = a2 + kstep; const char* b3 = b2 + kstep;
;             if (last && has_next) S.a_ready(nxt);
;             if constexpr (SP2) {
;             PG8_LDB(B0, 0, 0); PG8_LDB(B1, 0, 1); PG8_SCHED; PG8_LDA(At, 0, 0); PG8_STAGE(PG8_SA(1, 1), a1 + hstep, voffA);
;             PG8_WAIT_V(8); PG8_WAIT_L(0); PG8_BAR; PG8_MMA(0, 0, At, B0); PG8_MMA(0, 1, At, B1); PG8_BAR; PG8_SCHED;
;             PG8_LDA(At, 0, 1); PG8_STAGE(PG8_SB(0, 0), b2, voffB); PG8_STAGE(PG8_SB(0, 1), b2 + hstep, voffB); PG8_STAGE(PG8_SA(0, 0), a2, voffA);
;             PG8_WAIT_V(8); PG8_WAIT_L(0); PG8_BAR; PG8_MMA(1, 0, At, B0); PG8_MMA(1, 1, At, B1); PG8_BAR; PG8_SCHED;
.LBB11_1896:
	s_add_i32 s56, s22, 2
	s_add_u32 s57, s16, s20
	s_addc_u32 s23, s17, s21
	s_add_u32 s58, s14, s20
	s_addc_u32 s59, s15, s21
	s_add_i32 s60, 0, 0x10000
	s_cmp_eq_u32 s49, s22
	s_cselect_b32 s23, s5, s23
	s_cselect_b32 s22, s4, s57
	s_cselect_b32 s59, s19, s59
	s_cselect_b32 s58, s18, s58
	s_add_i32 s57, 0, 0x14000
	v_add_u32_e32 v156, s60, v1
	v_add_u32_e32 v174, s57, v1
	ds_read_b128 v[144:147], v156
	ds_read_b128 v[148:151], v156 offset:1024
	ds_read_b128 v[152:155], v156 offset:2048
	ds_read_b128 v[156:159], v156 offset:3072
	ds_read_b128 v[160:163], v174
	ds_read_b128 v[166:169], v174 offset:1024
	ds_read_b128 v[170:173], v174 offset:2048
	ds_read_b128 v[174:177], v174 offset:3072
	v_lshl_add_u64 v[184:185], s[16:17], 0, v[140:141]
	s_add_i32 m0, s45, 0xc000
	ds_read_b128 v[178:181], v143
	ds_read_b128 v[198:201], v143 offset:1024
	ds_read_b128 v[202:205], v143 offset:2048
	ds_read_b128 v[220:223], v143 offset:3072
	ds_read_b128 v[224:227], v143 offset:4096
	ds_read_b128 v[228:231], v143 offset:5120
	ds_read_b128 v[232:235], v143 offset:6144
	ds_read_b128 v[236:239], v143 offset:7168
	global_load_lds_dwordx4 v[184:185], off
	v_lshl_add_u64 v[184:185], s[16:17], 0, v[138:139]
	s_add_i32 m0, s45, 0xe000
	s_nop 0
	global_load_lds_dwordx4 v[184:185], off
	s_waitcnt vmcnt(8)
	s_waitcnt lgkmcnt(0)
	s_barrier
	s_setprio 1
	s_waitcnt lgkmcnt(0)
	v_mfma_f32_16x16x32_bf16 v[100:103], v[144:147], v[178:181], v[100:103]
	v_mfma_f32_16x16x32_bf16 v[100:103], v[148:151], v[198:201], v[100:103]
	v_mfma_f32_16x16x32_bf16 v[116:119], v[148:151], v[220:223], v[116:119]
	v_mfma_f32_16x16x32_bf16 v[116:119], v[144:147], v[202:205], v[116:119]
	v_mfma_f32_16x16x32_bf16 v[124:127], v[144:147], v[224:227], v[124:127]
	v_mfma_f32_16x16x32_bf16 v[124:127], v[148:151], v[228:231], v[124:127]
	v_mfma_f32_16x16x32_bf16 v[128:131], v[148:151], v[236:239], v[128:131]
	v_mfma_f32_16x16x32_bf16 v[128:131], v[144:147], v[232:235], v[128:131]
	v_mfma_f32_16x16x32_bf16 v[68:71], v[152:155], v[178:181], v[68:71]
	v_mfma_f32_16x16x32_bf16 v[68:71], v[156:159], v[198:201], v[68:71]
	v_mfma_f32_16x16x32_bf16 v[80:83], v[156:159], v[220:223], v[80:83]
	v_mfma_f32_16x16x32_bf16 v[80:83], v[152:155], v[202:205], v[80:83]
	v_mfma_f32_16x16x32_bf16 v[104:107], v[152:155], v[224:227], v[104:107]
	v_mfma_f32_16x16x32_bf16 v[104:107], v[156:159], v[228:231], v[104:107]
	v_mfma_f32_16x16x32_bf16 v[120:123], v[156:159], v[236:239], v[120:123]
	v_mfma_f32_16x16x32_bf16 v[120:123], v[152:155], v[232:235], v[120:123]
	s_setprio 0
	s_setprio 1
	v_mfma_f32_16x16x32_bf16 v[16:19], v[160:163], v[178:181], v[16:19]
	v_mfma_f32_16x16x32_bf16 v[16:19], v[166:169], v[198:201], v[16:19]
	v_mfma_f32_16x16x32_bf16 v[32:35], v[166:169], v[220:223], v[32:35]
	v_mfma_f32_16x16x32_bf16 v[32:35], v[160:163], v[202:205], v[32:35]
	v_mfma_f32_16x16x32_bf16 v[48:51], v[160:163], v[224:227], v[48:51]
	v_mfma_f32_16x16x32_bf16 v[48:51], v[166:169], v[228:231], v[48:51]
	v_mfma_f32_16x16x32_bf16 v[76:79], v[166:169], v[236:239], v[76:79]
	v_mfma_f32_16x16x32_bf16 v[76:79], v[160:163], v[232:235], v[76:79]
	v_mfma_f32_16x16x32_bf16 v[4:7], v[170:173], v[178:181], v[4:7]
	v_mfma_f32_16x16x32_bf16 v[4:7], v[174:177], v[198:201], v[4:7]
	v_mfma_f32_16x16x32_bf16 v[8:11], v[174:177], v[220:223], v[8:11]
	v_mfma_f32_16x16x32_bf16 v[8:11], v[170:173], v[202:205], v[8:11]
	v_mfma_f32_16x16x32_bf16 v[12:15], v[170:173], v[224:227], v[12:15]
	v_mfma_f32_16x16x32_bf16 v[12:15], v[174:177], v[228:231], v[12:15]
	v_mfma_f32_16x16x32_bf16 v[24:27], v[174:177], v[236:239], v[24:27]
	v_mfma_f32_16x16x32_bf16 v[24:27], v[170:173], v[232:235], v[24:27]
	s_setprio 0
	s_barrier
	s_add_i32 s60, s60, s13
	v_lshl_add_u64 v[184:185], s[58:59], 0, v[2:3]
	s_mov_b32 m0, s60
	ds_read_b128 v[178:181], v143 offset:16384
	ds_read_b128 v[198:201], v143 offset:17408
	ds_read_b128 v[202:205], v143 offset:18432
	ds_read_b128 v[220:223], v143 offset:19456
	ds_read_b128 v[224:227], v143 offset:20480
	ds_read_b128 v[228:231], v143 offset:21504
	ds_read_b128 v[232:235], v143 offset:22528
	ds_read_b128 v[236:239], v143 offset:23552
	global_load_lds_dwordx4 v[184:185], off
	s_add_i32 m0, s60, 0x2000
	v_lshl_add_u64 v[186:187], s[58:59], 0, v[132:133]
	s_add_u32 s58, s58, s33
	s_addc_u32 s59, s59, 0
	s_add_i32 s57, s57, s13
	global_load_lds_dwordx4 v[186:187], off
	v_lshl_add_u64 v[196:197], s[58:59], 0, v[2:3]
	s_mov_b32 m0, s57
	v_lshl_add_u64 v[206:207], s[58:59], 0, v[132:133]
	global_load_lds_dwordx4 v[196:197], off
	s_add_i32 m0, s57, 0x2000
	v_lshl_add_u64 v[240:241], s[22:23], 0, v[2:3]
	global_load_lds_dwordx4 v[206:207], off
	s_mov_b32 m0, s45
	v_lshl_add_u64 v[242:243], s[22:23], 0, v[132:133]
	global_load_lds_dwordx4 v[240:241], off
	s_mov_b32 m0, s46
	s_nop 0
	global_load_lds_dwordx4 v[242:243], off
	s_waitcnt vmcnt(8)
	s_waitcnt lgkmcnt(0)
	s_barrier
; #define PG8_STAGE(bufoff, gbase, voff) do { _Pragma("unroll") for (int _i = 0; _i < 2; ++_i) \
;         __builtin_amdgcn_global_load_lds((const unsigned*)((const char*)(gbase) + (voff)[_i]), (PG8_LAS unsigned*)(lds + (bufoff) + ldsw + _i * 8192), 16, 0, 0); } while (0)
; #define PG8_LDA(dst, b, h) do { _Pragma("unroll") for (int m = 0; m < 4; ++m) _Pragma("unroll") for (int k = 0; k < 2; ++k) dst[m][k] = *(const PG8_LAS bf16x8*)(lds + PG8_SA(b, h) + aoff + m * 2048 + k * 1024); } while (0)
; #define PG8_LDB(dst, b, h) do { _Pragma("unroll") for (int n = 0; n < 2; ++n) _Pragma("unroll") for (int k = 0; k < 2; ++k) dst[n][k] = *(const PG8_LAS bf16x8*)(lds + PG8_SB(b, h) + boff + n * 2048 + k * 1024); } while (0)
; #define PG8_MMA(ai, bj, At, Bt) do { __builtin_amdgcn_s_setprio(1); _Pragma("unroll") for (int m = 0; m < 4; ++m) _Pragma("unroll") for (int n = 0; n < 2; ++n) _Pragma("unroll") for (int k = 0; k < 2; ++k) \
;         acc[ai][bj][m][n] = __builtin_amdgcn_mfma_f32_16x16x32_bf16(Bt[n][k], At[m][k], acc[ai][bj][m][n], 0, 0, 0); __builtin_amdgcn_s_setprio(0); } while (0)
; #define PG8_WAIT_V(n) asm volatile("s_waitcnt vmcnt(" #n ")" ::: "memory")
; #define PG8_WAIT_L(n) asm volatile("s_waitcnt lgkmcnt(" #n ")" ::: "memory")
; #define PG8_BAR __builtin_amdgcn_s_barrier()
; #define PG8_SCHED __builtin_amdgcn_sched_barrier(0)
; template <class Epi, class Sched, bool ALIGN_EPI = false, bool SP2 = false>
; __device__ __forceinline__ void gemm_phase(PG8_LAS unsigned char* lds, const Gemm g, const Sched& S, const Epi& E) {
;     ...
;             PG8_WAIT_V(8); PG8_WAIT_L(0); PG8_BAR; PG8_MMA(1, 0, At, B0); PG8_MMA(1, 1, At, B1); PG8_BAR; PG8_SCHED;
;             PG8_LDB(B0, 1, 0); PG8_LDB(B1, 1, 1); PG8_SCHED; PG8_LDA(At, 1, 0); PG8_STAGE(PG8_SA(0, 1), a2 + hstep, voffA);
;             PG8_WAIT_V(8); PG8_WAIT_L(0); PG8_BAR; PG8_MMA(0, 0, At, B0); PG8_MMA(0, 1, At, B1); PG8_BAR; PG8_SCHED;
	s_setprio 1
	s_waitcnt lgkmcnt(0)
	v_mfma_f32_16x16x32_bf16 v[108:111], v[144:147], v[178:181], v[108:111]
	v_mfma_f32_16x16x32_bf16 v[108:111], v[148:151], v[198:201], v[108:111]
	v_mfma_f32_16x16x32_bf16 v[88:91], v[148:151], v[220:223], v[88:91]
	v_mfma_f32_16x16x32_bf16 v[88:91], v[144:147], v[202:205], v[88:91]
	v_mfma_f32_16x16x32_bf16 v[60:63], v[144:147], v[224:227], v[60:63]
	v_mfma_f32_16x16x32_bf16 v[60:63], v[148:151], v[228:231], v[60:63]
	v_mfma_f32_16x16x32_bf16 v[36:39], v[148:151], v[236:239], v[36:39]
	v_mfma_f32_16x16x32_bf16 v[36:39], v[144:147], v[232:235], v[36:39]
	v_mfma_f32_16x16x32_bf16 v[112:115], v[152:155], v[178:181], v[112:115]
	v_mfma_f32_16x16x32_bf16 v[112:115], v[156:159], v[198:201], v[112:115]
	v_mfma_f32_16x16x32_bf16 v[92:95], v[156:159], v[220:223], v[92:95]
	v_mfma_f32_16x16x32_bf16 v[92:95], v[152:155], v[202:205], v[92:95]
	v_mfma_f32_16x16x32_bf16 v[64:67], v[152:155], v[224:227], v[64:67]
	v_mfma_f32_16x16x32_bf16 v[64:67], v[156:159], v[228:231], v[64:67]
	v_mfma_f32_16x16x32_bf16 v[40:43], v[156:159], v[236:239], v[40:43]
	v_mfma_f32_16x16x32_bf16 v[40:43], v[152:155], v[232:235], v[40:43]
	s_setprio 0
	s_setprio 1
	v_mfma_f32_16x16x32_bf16 v[96:99], v[160:163], v[178:181], v[96:99]
	v_mfma_f32_16x16x32_bf16 v[96:99], v[166:169], v[198:201], v[96:99]
	v_mfma_f32_16x16x32_bf16 v[84:87], v[166:169], v[220:223], v[84:87]
	v_mfma_f32_16x16x32_bf16 v[84:87], v[160:163], v[202:205], v[84:87]
	v_mfma_f32_16x16x32_bf16 v[56:59], v[160:163], v[224:227], v[56:59]
	v_mfma_f32_16x16x32_bf16 v[56:59], v[166:169], v[228:231], v[56:59]
	v_mfma_f32_16x16x32_bf16 v[28:31], v[166:169], v[236:239], v[28:31]
	v_mfma_f32_16x16x32_bf16 v[28:31], v[160:163], v[232:235], v[28:31]
	v_mfma_f32_16x16x32_bf16 v[44:47], v[170:173], v[178:181], v[44:47]
	v_mfma_f32_16x16x32_bf16 v[44:47], v[174:177], v[198:201], v[44:47]
	v_mfma_f32_16x16x32_bf16 v[72:75], v[174:177], v[220:223], v[72:75]
	v_mfma_f32_16x16x32_bf16 v[72:75], v[170:173], v[202:205], v[72:75]
	v_mfma_f32_16x16x32_bf16 v[52:55], v[170:173], v[224:227], v[52:55]
	v_mfma_f32_16x16x32_bf16 v[52:55], v[174:177], v[228:231], v[52:55]
	v_mfma_f32_16x16x32_bf16 v[20:23], v[174:177], v[236:239], v[20:23]
	v_mfma_f32_16x16x32_bf16 v[20:23], v[170:173], v[232:235], v[20:23]
	s_setprio 0
	s_barrier
	s_add_i32 s57, 0, 0x18000
	s_add_i32 s58, 0, 0x1c000
	v_add_u32_e32 v156, s57, v1
	v_add_u32_e32 v174, s58, v1
	ds_read_b128 v[144:147], v156
	ds_read_b128 v[148:151], v156 offset:1024
	ds_read_b128 v[152:155], v156 offset:2048
	ds_read_b128 v[156:159], v156 offset:3072
	ds_read_b128 v[160:163], v174
	ds_read_b128 v[166:169], v174 offset:1024
	ds_read_b128 v[170:173], v174 offset:2048
	ds_read_b128 v[174:177], v174 offset:3072
	s_add_u32 s22, s22, s33
	s_addc_u32 s23, s23, 0
	s_mov_b32 m0, s47
	v_lshl_add_u64 v[244:245], s[22:23], 0, v[2:3]
	ds_read_b128 v[178:181], v143 offset:32768
	ds_read_b128 v[198:201], v143 offset:33792
	ds_read_b128 v[202:205], v143 offset:34816
	ds_read_b128 v[220:223], v143 offset:35840
	ds_read_b128 v[224:227], v143 offset:36864
	ds_read_b128 v[228:231], v143 offset:37888
	ds_read_b128 v[232:235], v143 offset:38912
	ds_read_b128 v[236:239], v143 offset:39936
	global_load_lds_dwordx4 v[244:245], off
	v_lshl_add_u64 v[244:245], s[22:23], 0, v[132:133]
	s_mov_b32 m0, s48
	s_nop 0
	global_load_lds_dwordx4 v[244:245], off
	s_waitcnt vmcnt(8)
	s_waitcnt lgkmcnt(0)
	s_barrier
	s_setprio 1
	s_waitcnt lgkmcnt(0)
	v_mfma_f32_16x16x32_bf16 v[100:103], v[144:147], v[178:181], v[100:103]
	v_mfma_f32_16x16x32_bf16 v[100:103], v[148:151], v[198:201], v[100:103]
	v_mfma_f32_16x16x32_bf16 v[116:119], v[148:151], v[220:223], v[116:119]
	v_mfma_f32_16x16x32_bf16 v[116:119], v[144:147], v[202:205], v[116:119]
	v_mfma_f32_16x16x32_bf16 v[124:127], v[144:147], v[224:227], v[124:127]
	v_mfma_f32_16x16x32_bf16 v[124:127], v[148:151], v[228:231], v[124:127]
	v_mfma_f32_16x16x32_bf16 v[128:131], v[148:151], v[236:239], v[128:131]
	v_mfma_f32_16x16x32_bf16 v[128:131], v[144:147], v[232:235], v[128:131]
	v_mfma_f32_16x16x32_bf16 v[68:71], v[152:155], v[178:181], v[68:71]
	v_mfma_f32_16x16x32_bf16 v[68:71], v[156:159], v[198:201], v[68:71]
	v_mfma_f32_16x16x32_bf16 v[80:83], v[156:159], v[220:223], v[80:83]
	v_mfma_f32_16x16x32_bf16 v[80:83], v[152:155], v[202:205], v[80:83]
	v_mfma_f32_16x16x32_bf16 v[104:107], v[152:155], v[224:227], v[104:107]
	v_mfma_f32_16x16x32_bf16 v[104:107], v[156:159], v[228:231], v[104:107]
	v_mfma_f32_16x16x32_bf16 v[120:123], v[156:159], v[236:239], v[120:123]
	v_mfma_f32_16x16x32_bf16 v[120:123], v[152:155], v[232:235], v[120:123]
	s_setprio 0
	s_setprio 1
	v_mfma_f32_16x16x32_bf16 v[16:19], v[160:163], v[178:181], v[16:19]
	v_mfma_f32_16x16x32_bf16 v[16:19], v[166:169], v[198:201], v[16:19]
	v_mfma_f32_16x16x32_bf16 v[32:35], v[166:169], v[220:223], v[32:35]
	v_mfma_f32_16x16x32_bf16 v[32:35], v[160:163], v[202:205], v[32:35]
	v_mfma_f32_16x16x32_bf16 v[48:51], v[160:163], v[224:227], v[48:51]
	v_mfma_f32_16x16x32_bf16 v[48:51], v[166:169], v[228:231], v[48:51]
	v_mfma_f32_16x16x32_bf16 v[76:79], v[166:169], v[236:239], v[76:79]
	v_mfma_f32_16x16x32_bf16 v[76:79], v[160:163], v[232:235], v[76:79]
	v_mfma_f32_16x16x32_bf16 v[4:7], v[170:173], v[178:181], v[4:7]
	v_mfma_f32_16x16x32_bf16 v[4:7], v[174:177], v[198:201], v[4:7]
	v_mfma_f32_16x16x32_bf16 v[8:11], v[174:177], v[220:223], v[8:11]
	v_mfma_f32_16x16x32_bf16 v[8:11], v[170:173], v[202:205], v[8:11]
	v_mfma_f32_16x16x32_bf16 v[12:15], v[170:173], v[224:227], v[12:15]
	v_mfma_f32_16x16x32_bf16 v[12:15], v[174:177], v[228:231], v[12:15]
	v_mfma_f32_16x16x32_bf16 v[24:27], v[174:177], v[236:239], v[24:27]
	v_mfma_f32_16x16x32_bf16 v[24:27], v[170:173], v[232:235], v[24:27]
	s_setprio 0
	s_barrier
; #define PG8_STAGE(bufoff, gbase, voff) do { _Pragma("unroll") for (int _i = 0; _i < 2; ++_i) \
;         __builtin_amdgcn_global_load_lds((const unsigned*)((const char*)(gbase) + (voff)[_i]), (PG8_LAS unsigned*)(lds + (bufoff) + ldsw + _i * 8192), 16, 0, 0); } while (0)
; #define PG8_LDA(dst, b, h) do { _Pragma("unroll") for (int m = 0; m < 4; ++m) _Pragma("unroll") for (int k = 0; k < 2; ++k) dst[m][k] = *(const PG8_LAS bf16x8*)(lds + PG8_SA(b, h) + aoff + m * 2048 + k * 1024); } while (0)
; #define PG8_MMA(ai, bj, At, Bt) do { __builtin_amdgcn_s_setprio(1); _Pragma("unroll") for (int m = 0; m < 4; ++m) _Pragma("unroll") for (int n = 0; n < 2; ++n) _Pragma("unroll") for (int k = 0; k < 2; ++k) \
;         acc[ai][bj][m][n] = __builtin_amdgcn_mfma_f32_16x16x32_bf16(Bt[n][k], At[m][k], acc[ai][bj][m][n], 0, 0, 0); __builtin_amdgcn_s_setprio(0); } while (0)
; #define PG8_WAIT_V(n) asm volatile("s_waitcnt vmcnt(" #n ")" ::: "memory")
; #define PG8_WAIT_L(n) asm volatile("s_waitcnt lgkmcnt(" #n ")" ::: "memory")
; #define PG8_BAR __builtin_amdgcn_s_barrier()
; #define PG8_SCHED __builtin_amdgcn_sched_barrier(0)
; template <class Epi, class Sched, bool ALIGN_EPI = false, bool SP2 = false>
; __device__ __forceinline__ void gemm_phase(PG8_LAS unsigned char* lds, const Gemm g, const Sched& S, const Epi& E) {
;     ...
;             PG8_LDA(At, 1, 1); PG8_STAGE(PG8_SB(1, 0), b3, voffB); PG8_STAGE(PG8_SB(1, 1), b3 + hstep, voffB); PG8_STAGE(PG8_SA(1, 0), a3, voffA);
;             PG8_WAIT_V(8); PG8_WAIT_L(0); PG8_BAR; PG8_MMA(1, 0, At, B0); PG8_MMA(1, 1, At, B1); PG8_BAR; PG8_SCHED;
;     ...
;         if (!has_next) break;
; #pragma unroll
;         for (int a = 0; a < 2; ++a)
; #pragma unroll
;             for (int b = 0; b < 2; ++b)
; #pragma unroll
;                 for (int m = 0; m < 4; ++m)
; #pragma unroll
;                     for (int n = 0; n < 2; ++n) acc[a][b][m][n] = (f32x4){0.f, 0.f, 0.f, 0.f};
;         cur = nxt; cA = nA; cB = nB; ++ui;
	s_add_i32 s22, s57, s13
	v_lshl_add_u64 v[184:185], v[184:185], 0, s[34:35]
	s_mov_b32 m0, s22
	ds_read_b128 v[178:181], v143 offset:49152
	ds_read_b128 v[198:201], v143 offset:50176
	ds_read_b128 v[202:205], v143 offset:51200
	ds_read_b128 v[220:223], v143 offset:52224
	ds_read_b128 v[224:227], v143 offset:53248
	ds_read_b128 v[228:231], v143 offset:54272
	ds_read_b128 v[232:235], v143 offset:55296
	ds_read_b128 v[236:239], v143 offset:56320
	global_load_lds_dwordx4 v[184:185], off
	v_lshl_add_u64 v[184:185], v[186:187], 0, s[34:35]
	s_add_i32 m0, s22, 0x2000
	s_add_i32 s22, s58, s13
	global_load_lds_dwordx4 v[184:185], off
	v_lshl_add_u64 v[184:185], v[196:197], 0, s[34:35]
	s_mov_b32 m0, s22
	s_nop 0
	global_load_lds_dwordx4 v[184:185], off
	v_lshl_add_u64 v[184:185], v[206:207], 0, s[34:35]
	s_add_i32 m0, s22, 0x2000
	s_nop 0
	global_load_lds_dwordx4 v[184:185], off
	v_lshl_add_u64 v[184:185], v[240:241], 0, s[34:35]
	s_mov_b32 m0, s50
	s_nop 0
	global_load_lds_dwordx4 v[184:185], off
	v_lshl_add_u64 v[184:185], v[242:243], 0, s[34:35]
	s_mov_b32 m0, s51
	s_nop 0
	global_load_lds_dwordx4 v[184:185], off
	s_waitcnt vmcnt(8)
	s_waitcnt lgkmcnt(0)
	s_barrier
	s_setprio 1
	s_waitcnt lgkmcnt(0)
	v_mfma_f32_16x16x32_bf16 v[108:111], v[144:147], v[178:181], v[108:111]
	v_mfma_f32_16x16x32_bf16 v[108:111], v[148:151], v[198:201], v[108:111]
	v_mfma_f32_16x16x32_bf16 v[88:91], v[148:151], v[220:223], v[88:91]
	v_mfma_f32_16x16x32_bf16 v[88:91], v[144:147], v[202:205], v[88:91]
	v_mfma_f32_16x16x32_bf16 v[60:63], v[144:147], v[224:227], v[60:63]
	v_mfma_f32_16x16x32_bf16 v[60:63], v[148:151], v[228:231], v[60:63]
	v_mfma_f32_16x16x32_bf16 v[36:39], v[148:151], v[236:239], v[36:39]
	v_mfma_f32_16x16x32_bf16 v[36:39], v[144:147], v[232:235], v[36:39]
	v_mfma_f32_16x16x32_bf16 v[112:115], v[152:155], v[178:181], v[112:115]
	v_mfma_f32_16x16x32_bf16 v[112:115], v[156:159], v[198:201], v[112:115]
	v_mfma_f32_16x16x32_bf16 v[92:95], v[156:159], v[220:223], v[92:95]
	v_mfma_f32_16x16x32_bf16 v[92:95], v[152:155], v[202:205], v[92:95]
	v_mfma_f32_16x16x32_bf16 v[64:67], v[152:155], v[224:227], v[64:67]
	v_mfma_f32_16x16x32_bf16 v[64:67], v[156:159], v[228:231], v[64:67]
	v_mfma_f32_16x16x32_bf16 v[40:43], v[156:159], v[236:239], v[40:43]
	v_mfma_f32_16x16x32_bf16 v[40:43], v[152:155], v[232:235], v[40:43]
	s_setprio 0
	s_setprio 1
	v_mfma_f32_16x16x32_bf16 v[96:99], v[160:163], v[178:181], v[96:99]
	v_mfma_f32_16x16x32_bf16 v[96:99], v[166:169], v[198:201], v[96:99]
	v_mfma_f32_16x16x32_bf16 v[84:87], v[166:169], v[220:223], v[84:87]
	v_mfma_f32_16x16x32_bf16 v[84:87], v[160:163], v[202:205], v[84:87]
	v_mfma_f32_16x16x32_bf16 v[56:59], v[160:163], v[224:227], v[56:59]
	v_mfma_f32_16x16x32_bf16 v[56:59], v[166:169], v[228:231], v[56:59]
	v_mfma_f32_16x16x32_bf16 v[28:31], v[166:169], v[236:239], v[28:31]
	v_mfma_f32_16x16x32_bf16 v[28:31], v[160:163], v[232:235], v[28:31]
	v_mfma_f32_16x16x32_bf16 v[44:47], v[170:173], v[178:181], v[44:47]
	v_mfma_f32_16x16x32_bf16 v[44:47], v[174:177], v[198:201], v[44:47]
	v_mfma_f32_16x16x32_bf16 v[72:75], v[174:177], v[220:223], v[72:75]
	v_mfma_f32_16x16x32_bf16 v[72:75], v[170:173], v[202:205], v[72:75]
	v_mfma_f32_16x16x32_bf16 v[52:55], v[170:173], v[224:227], v[52:55]
	v_mfma_f32_16x16x32_bf16 v[52:55], v[174:177], v[228:231], v[52:55]
	v_mfma_f32_16x16x32_bf16 v[20:23], v[174:177], v[236:239], v[20:23]
	v_mfma_f32_16x16x32_bf16 v[20:23], v[170:173], v[232:235], v[20:23]
	s_setprio 0
	s_barrier
	s_add_u32 s20, s20, 0x100
	s_addc_u32 s21, s21, 0
	v_lshl_add_u64 v[140:141], v[140:141], 0, s[62:63]
	v_lshl_add_u64 v[138:139], v[138:139], 0, s[62:63]
	s_cmp_ge_u32 s56, s29
	s_mov_b32 s22, s56
	s_cbranch_scc0 .LBB11_1896
	s_and_b64 vcc, exec, s[38:39]
	s_cbranch_vccnz .LBB11_1884
	v_mov_b32_e32 v20, 0
	s_mov_b32 s42, s53
	s_mov_b32 s28, s54
	s_mov_b64 s[14:15], s[18:19]
	s_mov_b64 s[16:17], s[4:5]
	s_mov_b32 s52, s55
	v_mov_b32_e32 v21, v20
	v_mov_b32_e32 v22, v20
	v_mov_b32_e32 v23, v20
	v_mov_b32_e32 v28, v20
	v_mov_b32_e32 v29, v20
	v_mov_b32_e32 v30, v20
	v_mov_b32_e32 v31, v20
	v_mov_b32_e32 v52, v20
	v_mov_b32_e32 v53, v20
	v_mov_b32_e32 v54, v20
	v_mov_b32_e32 v55, v20
	v_mov_b32_e32 v56, v20
	v_mov_b32_e32 v57, v20
	v_mov_b32_e32 v58, v20
	v_mov_b32_e32 v59, v20
	v_mov_b32_e32 v72, v20
	v_mov_b32_e32 v73, v20
	v_mov_b32_e32 v74, v20
	v_mov_b32_e32 v75, v20
	v_mov_b32_e32 v84, v20
	v_mov_b32_e32 v85, v20
	v_mov_b32_e32 v86, v20
	v_mov_b32_e32 v87, v20
	v_mov_b32_e32 v44, v20
	v_mov_b32_e32 v45, v20
	v_mov_b32_e32 v46, v20
	v_mov_b32_e32 v47, v20
	v_mov_b32_e32 v96, v20
	v_mov_b32_e32 v97, v20
	v_mov_b32_e32 v98, v20
	v_mov_b32_e32 v99, v20
	v_mov_b32_e32 v40, v20
	v_mov_b32_e32 v41, v20
	v_mov_b32_e32 v42, v20
	v_mov_b32_e32 v43, v20
	v_mov_b32_e32 v36, v20
	v_mov_b32_e32 v37, v20
	v_mov_b32_e32 v38, v20
	v_mov_b32_e32 v39, v20
	v_mov_b32_e32 v64, v20
	v_mov_b32_e32 v65, v20
	v_mov_b32_e32 v66, v20
	v_mov_b32_e32 v67, v20
	v_mov_b32_e32 v60, v20
	v_mov_b32_e32 v61, v20
	v_mov_b32_e32 v62, v20
	v_mov_b32_e32 v63, v20
	v_mov_b32_e32 v92, v20
	v_mov_b32_e32 v93, v20
	v_mov_b32_e32 v94, v20
	v_mov_b32_e32 v95, v20
	v_mov_b32_e32 v88, v20
	v_mov_b32_e32 v89, v20
	v_mov_b32_e32 v90, v20
	v_mov_b32_e32 v91, v20
	v_mov_b32_e32 v112, v20
	v_mov_b32_e32 v113, v20
	v_mov_b32_e32 v114, v20
	v_mov_b32_e32 v115, v20
	v_mov_b32_e32 v108, v20
	v_mov_b32_e32 v109, v20
	v_mov_b32_e32 v110, v20
	v_mov_b32_e32 v111, v20
	v_mov_b32_e32 v24, v20
	v_mov_b32_e32 v25, v20
	v_mov_b32_e32 v26, v20
	v_mov_b32_e32 v27, v20
	v_mov_b32_e32 v76, v20
	v_mov_b32_e32 v77, v20
	v_mov_b32_e32 v78, v20
	v_mov_b32_e32 v79, v20
	v_mov_b32_e32 v12, v20
	v_mov_b32_e32 v13, v20
	v_mov_b32_e32 v14, v20
	v_mov_b32_e32 v15, v20
	v_mov_b32_e32 v48, v20
	v_mov_b32_e32 v49, v20
	v_mov_b32_e32 v50, v20
	v_mov_b32_e32 v51, v20
	v_mov_b32_e32 v8, v20
	v_mov_b32_e32 v9, v20
	v_mov_b32_e32 v10, v20
	v_mov_b32_e32 v11, v20
	v_mov_b32_e32 v32, v20
	v_mov_b32_e32 v33, v20
	v_mov_b32_e32 v34, v20
	v_mov_b32_e32 v35, v20
	v_mov_b32_e32 v4, v20
	v_mov_b32_e32 v5, v20
	v_mov_b32_e32 v6, v20
	v_mov_b32_e32 v7, v20
	v_mov_b32_e32 v16, v20
	v_mov_b32_e32 v17, v20
	v_mov_b32_e32 v18, v20
	v_mov_b32_e32 v19, v20
	v_mov_b32_e32 v120, v20
	v_mov_b32_e32 v121, v20
	v_mov_b32_e32 v122, v20
	v_mov_b32_e32 v123, v20
	v_mov_b32_e32 v128, v20
	v_mov_b32_e32 v129, v20
	v_mov_b32_e32 v130, v20
	v_mov_b32_e32 v131, v20
	v_mov_b32_e32 v104, v20
	v_mov_b32_e32 v105, v20
	v_mov_b32_e32 v106, v20
	v_mov_b32_e32 v107, v20
	v_mov_b32_e32 v124, v20
	v_mov_b32_e32 v125, v20
	v_mov_b32_e32 v126, v20
	v_mov_b32_e32 v127, v20
	v_mov_b32_e32 v80, v20
	v_mov_b32_e32 v81, v20
	v_mov_b32_e32 v82, v20
	v_mov_b32_e32 v83, v20
	v_mov_b32_e32 v116, v20
	v_mov_b32_e32 v117, v20
	v_mov_b32_e32 v118, v20
	v_mov_b32_e32 v119, v20
	v_mov_b32_e32 v68, v20
	v_mov_b32_e32 v69, v20
	v_mov_b32_e32 v70, v20
	v_mov_b32_e32 v71, v20
	v_mov_b32_e32 v100, v20
	v_mov_b32_e32 v101, v20
	v_mov_b32_e32 v102, v20
	v_mov_b32_e32 v103, v20
	s_branch .LBB11_1884
